# rownorm x3: cross-iteration software pipeline (next 4 rows' 16 loads issued into a second register set before current reduce/store tail)
# baseline (speedup 1.0000x reference)
.LBB0_388:
	v_add_u32_e32 v0, s18, v58
	v_cmp_gt_i32_e64 s[8:9], s3, v0
	v_lshrrev_b32_e32 v69, 3, v58
	v_and_b32_e32 v59, 0x700, v66
	v_cndmask_b32_e64 v1, v58, v0, s[8:9]
	v_lshlrev_b32_e32 v2, 5, v1
	v_lshrrev_b32_e32 v3, 3, v1
	v_and_b32_e32 v2, 0x700, v2
	v_and_b32_e32 v3, 0xf8, v3
	v_and_b32_e32 v4, 0xfffff807, v1
	v_or3_b32 v2, v2, v4, v3
	v_cndmask_b32_e32 v56, v1, v2, vcc
	v_add_u32_e32 v2, s18, v0
	v_cmp_gt_i32_e64 s[4:5], s3, v2
	v_ashrrev_i32_e32 v57, 31, v56
	v_add_u32_e32 v68, s18, v2
	v_cndmask_b32_e64 v3, v58, v2, s[4:5]
	v_lshlrev_b32_e32 v0, 5, v3
	v_and_b32_e32 v4, 0x700, v0
	v_lshlrev_b64 v[0:1], 12, v[56:57]
	v_lshl_add_u64 v[0:1], v[50:51], 0, v[0:1]
	v_lshrrev_b32_e32 v5, 3, v3
	global_load_dwordx4 v[44:47], v[0:1], off
	global_load_dwordx4 v[40:43], v[0:1], off offset:1024
	v_and_b32_e32 v5, 0xf8, v5
	v_and_b32_e32 v6, 0xfffff807, v3
	global_load_dwordx4 v[36:39], v[0:1], off offset:2048
	global_load_dwordx4 v[32:35], v[0:1], off offset:3072
	v_or3_b32 v0, v4, v6, v5
	v_cndmask_b32_e32 v54, v3, v0, vcc
	v_ashrrev_i32_e32 v55, 31, v54
	v_lshlrev_b64 v[0:1], 12, v[54:55]
	v_lshl_add_u64 v[0:1], v[50:51], 0, v[0:1]
	v_cmp_gt_i32_e64 s[6:7], s3, v68
	global_load_dwordx4 v[28:31], v[0:1], off
	global_load_dwordx4 v[24:27], v[0:1], off offset:1024
	global_load_dwordx4 v[20:23], v[0:1], off offset:2048
	global_load_dwordx4 v[16:19], v[0:1], off offset:3072
	v_cndmask_b32_e64 v0, v58, v68, s[6:7]
	v_lshlrev_b32_e32 v1, 5, v0
	v_lshrrev_b32_e32 v2, 3, v0
	v_and_b32_e32 v3, 0xfffff807, v0
	v_and_b32_e32 v1, 0x700, v1
	v_and_b32_e32 v2, 0xf8, v2
	v_or3_b32 v1, v1, v3, v2
	v_cndmask_b32_e32 v52, v0, v1, vcc
	v_ashrrev_i32_e32 v53, 31, v52
	v_lshlrev_b64 v[0:1], 12, v[52:53]
	v_lshl_add_u64 v[0:1], v[50:51], 0, v[0:1]
	global_load_dwordx4 v[12:15], v[0:1], off
	global_load_dwordx4 v[8:11], v[0:1], off offset:1024
	global_load_dwordx4 v[4:7], v[0:1], off offset:2048
	s_nop 0
	global_load_dwordx4 v[0:3], v[0:1], off offset:3072
	s_waitcnt lgkmcnt(0)
	v_and_b32_e32 v70, 0xfffff807, v58
	v_and_b32_e32 v69, 0xf8, v69
	v_or3_b32 v59, v59, v70, v69
	v_cndmask_b32_e32 v58, v58, v59, vcc
	v_ashrrev_i32_e32 v59, 31, v58
	v_lshlrev_b64 v[70:71], 12, v[58:59]
	v_lshl_add_u64 v[70:71], v[50:51], 0, v[70:71]
	global_load_dwordx4 v[76:79], v[70:71], off
	global_load_dwordx4 v[80:83], v[70:71], off offset:1024
	global_load_dwordx4 v[84:87], v[70:71], off offset:2048
	global_load_dwordx4 v[88:91], v[70:71], off offset:3072
	v_lshlrev_b64 v[58:59], 11, v[58:59]
	v_lshl_add_u64 v[58:59], v[48:49], 0, v[58:59]
	v_add_u32_e32 v172, s18, v68
	v_add_u32_e32 v180, s19, v66
	v_cmp_ge_i32_e64 s[10:11], s23, v172
	s_nop 1
	s_and_b64 s[10:11], s[10:11], exec
	s_cbranch_scc0 .Lrnp1_orig
	v_add_u32_e32 v114, s18, v172
	v_cmp_gt_i32_e64 s[10:11], s3, v114
	v_lshrrev_b32_e32 v183, 3, v172
	v_and_b32_e32 v173, 0x700, v180
	v_cndmask_b32_e64 v115, v172, v114, s[10:11]
	v_lshlrev_b32_e32 v116, 5, v115
	v_lshrrev_b32_e32 v117, 3, v115
	v_and_b32_e32 v116, 0x700, v116
	v_and_b32_e32 v117, 0xf8, v117
	v_and_b32_e32 v118, 0xfffff807, v115
	v_or3_b32 v116, v116, v118, v117
	v_cndmask_b32_e32 v170, v115, v116, vcc
	v_add_u32_e32 v116, s18, v114
	v_cmp_gt_i32_e64 s[10:11], s3, v116
	v_ashrrev_i32_e32 v171, 31, v170
	v_add_u32_e32 v182, s18, v116
	v_cndmask_b32_e64 v117, v172, v116, s[10:11]
	v_lshlrev_b32_e32 v114, 5, v117
	v_and_b32_e32 v118, 0x700, v114
	v_lshlrev_b64 v[114:115], 12, v[170:171]
	v_lshl_add_u64 v[114:115], v[50:51], 0, v[114:115]
	v_lshrrev_b32_e32 v119, 3, v117
	global_load_dwordx4 v[158:161], v[114:115], off
	global_load_dwordx4 v[154:157], v[114:115], off offset:1024
	v_and_b32_e32 v119, 0xf8, v119
	v_and_b32_e32 v120, 0xfffff807, v117
	global_load_dwordx4 v[150:153], v[114:115], off offset:2048
	global_load_dwordx4 v[146:149], v[114:115], off offset:3072
	v_or3_b32 v114, v118, v120, v119
	v_cndmask_b32_e32 v168, v117, v114, vcc
	v_ashrrev_i32_e32 v169, 31, v168
	v_lshlrev_b64 v[114:115], 12, v[168:169]
	v_lshl_add_u64 v[114:115], v[50:51], 0, v[114:115]
	v_cmp_gt_i32_e64 s[10:11], s3, v182
	global_load_dwordx4 v[142:145], v[114:115], off
	global_load_dwordx4 v[138:141], v[114:115], off offset:1024
	global_load_dwordx4 v[134:137], v[114:115], off offset:2048
	global_load_dwordx4 v[130:133], v[114:115], off offset:3072
	v_cndmask_b32_e64 v114, v172, v182, s[10:11]
	v_lshlrev_b32_e32 v115, 5, v114
	v_lshrrev_b32_e32 v116, 3, v114
	v_and_b32_e32 v117, 0xfffff807, v114
	v_and_b32_e32 v115, 0x700, v115
	v_and_b32_e32 v116, 0xf8, v116
	v_or3_b32 v115, v115, v117, v116
	v_cndmask_b32_e32 v166, v114, v115, vcc
	v_ashrrev_i32_e32 v167, 31, v166
	v_lshlrev_b64 v[114:115], 12, v[166:167]
	v_lshl_add_u64 v[114:115], v[50:51], 0, v[114:115]
	global_load_dwordx4 v[126:129], v[114:115], off
	global_load_dwordx4 v[122:125], v[114:115], off offset:1024
	global_load_dwordx4 v[118:121], v[114:115], off offset:2048
	s_nop 0
	global_load_dwordx4 v[114:117], v[114:115], off offset:3072
	s_waitcnt lgkmcnt(0)
	v_and_b32_e32 v184, 0xfffff807, v172
	v_and_b32_e32 v183, 0xf8, v183
	v_or3_b32 v173, v173, v184, v183
	v_cndmask_b32_e32 v172, v172, v173, vcc
	v_ashrrev_i32_e32 v173, 31, v172
	v_lshlrev_b64 v[184:185], 12, v[172:173]
	v_lshl_add_u64 v[184:185], v[50:51], 0, v[184:185]
	global_load_dwordx4 v[190:193], v[184:185], off
	global_load_dwordx4 v[194:197], v[184:185], off offset:1024
	global_load_dwordx4 v[198:201], v[184:185], off offset:2048
	global_load_dwordx4 v[202:205], v[184:185], off offset:3072
	v_lshlrev_b64 v[172:173], 11, v[172:173]
	v_lshl_add_u64 v[172:173], v[48:49], 0, v[172:173]
	s_waitcnt vmcnt(31)
	v_pk_mul_f32 v[70:71], v[44:45], v[44:45]
	s_waitcnt vmcnt(30)
	v_pk_mul_f32 v[74:75], v[40:41], v[40:41]
	v_pk_mul_f32 v[72:73], v[46:47], v[46:47]
	v_pk_mul_f32 v[92:93], v[42:43], v[42:43]
	s_waitcnt vmcnt(29)
	v_pk_mul_f32 v[94:95], v[36:37], v[36:37]
	v_add_f32_e32 v69, v74, v75
	v_add_f32_e32 v110, v70, v71
	v_pk_mul_f32 v[96:97], v[38:39], v[38:39]
	s_waitcnt vmcnt(28)
	v_pk_mul_f32 v[98:99], v[32:33], v[32:33]
	v_add_f32_e32 v111, v94, v95
	v_add_f32_e32 v69, v69, v92
	v_add_f32_e32 v72, v110, v72
	v_pk_mul_f32 v[100:101], v[34:35], v[34:35]
	v_add_f32_e32 v112, v98, v99
	v_add_f32_e32 v92, v111, v96
	v_add_f32_e32 v69, v69, v93
	v_add_f32_e32 v72, v72, v73
	v_add_f32_e32 v96, v112, v100
	v_add_f32_e32 v73, v92, v97
	v_add_f32_e32 v69, v72, v69
	v_add_f32_e32 v92, v96, v101
	v_add_f32_e32 v69, v69, v73
	s_waitcnt vmcnt(27)
	v_pk_mul_f32 v[70:71], v[28:29], v[28:29]
	s_waitcnt vmcnt(25)
	v_pk_mul_f32 v[102:103], v[20:21], v[20:21]
	v_add_f32_e32 v69, v69, v92
	v_add_f32_e32 v70, v70, v71
	v_add_f32_e32 v71, v102, v103
	ds_bpermute_b32 v103, v60, v69
	v_pk_mul_f32 v[74:75], v[30:31], v[30:31]
	v_pk_mul_f32 v[94:95], v[24:25], v[24:25]
	v_pk_mul_f32 v[98:99], v[26:27], v[26:27]
	v_add_f32_e32 v94, v94, v95
	v_add_f32_e32 v70, v70, v74
	v_pk_mul_f32 v[104:105], v[22:23], v[22:23]
	v_add_f32_e32 v72, v94, v98
	v_add_f32_e32 v70, v70, v75
	s_waitcnt vmcnt(22)
	v_pk_mul_f32 v[74:75], v[8:9], v[8:9]
	s_waitcnt lgkmcnt(0)
	v_add_f32_e32 v69, v69, v103
	v_add_f32_e32 v72, v72, v99
	v_add_f32_e32 v71, v71, v104
	v_add_f32_e32 v74, v74, v75
	ds_bpermute_b32 v75, v61, v69
	v_pk_mul_f32 v[106:107], v[16:17], v[16:17]
	v_add_f32_e32 v70, v70, v72
	v_add_f32_e32 v71, v71, v105
	v_pk_mul_f32 v[108:109], v[18:19], v[18:19]
	v_add_f32_e32 v70, v70, v71
	v_add_f32_e32 v71, v106, v107
	v_add_f32_e32 v71, v71, v108
	v_add_f32_e32 v71, v71, v109
	v_add_f32_e32 v102, v70, v71
	v_pk_mul_f32 v[70:71], v[12:13], v[12:13]
	s_waitcnt lgkmcnt(0)
	v_add_f32_e32 v69, v69, v75
	v_add_f32_e32 v70, v70, v71
	ds_bpermute_b32 v71, v62, v69
	v_pk_mul_f32 v[72:73], v[14:15], v[14:15]
	v_pk_mul_f32 v[92:93], v[10:11], v[10:11]
	s_waitcnt vmcnt(21)
	v_pk_mul_f32 v[94:95], v[4:5], v[4:5]
	v_pk_mul_f32 v[96:97], v[6:7], v[6:7]
	s_waitcnt lgkmcnt(0)
	v_add_f32_e32 v69, v69, v71
	v_add_f32_e32 v74, v74, v92
	v_add_f32_e32 v70, v70, v72
	v_add_f32_e32 v72, v94, v95
	ds_bpermute_b32 v71, v63, v69
	v_add_f32_e32 v74, v74, v93
	v_add_f32_e32 v70, v70, v73
	v_add_f32_e32 v72, v72, v96
	s_waitcnt vmcnt(20)
	v_pk_mul_f32 v[98:99], v[0:1], v[0:1]
	v_add_f32_e32 v70, v70, v74
	v_add_f32_e32 v72, v72, v97
	v_pk_mul_f32 v[100:101], v[2:3], v[2:3]
	v_add_f32_e32 v96, v70, v72
	v_add_f32_e32 v70, v98, v99
	s_waitcnt vmcnt(19)
	v_mov_b32_e32 v92, v77
	s_waitcnt vmcnt(18)
	v_mov_b32_e32 v93, v81
	v_add_f32_e32 v70, v70, v100
	v_mov_b32_e32 v74, v76
	v_mov_b32_e32 v75, v80
	v_pk_mul_f32 v[92:93], v[92:93], v[92:93]
	v_add_f32_e32 v97, v70, v101
	s_waitcnt lgkmcnt(0)
	v_add_f32_e32 v69, v69, v71
	v_mov_b32_e32 v70, v78
	v_mov_b32_e32 v71, v82
	v_pk_fma_f32 v[74:75], v[74:75], v[74:75], v[92:93]
	s_waitcnt vmcnt(17)
	v_mov_b32_e32 v94, v85
	s_waitcnt vmcnt(16)
	v_mov_b32_e32 v95, v89
	v_mov_b32_e32 v72, v79
	v_mov_b32_e32 v73, v83
	v_pk_fma_f32 v[70:71], v[70:71], v[70:71], v[74:75]
	v_mov_b32_e32 v92, v84
	v_mov_b32_e32 v93, v88
	v_pk_mul_f32 v[94:95], v[94:95], v[94:95]
	v_pk_fma_f32 v[70:71], v[72:73], v[72:73], v[70:71]
	v_mov_b32_e32 v72, v86
	v_mov_b32_e32 v73, v90
	v_pk_fma_f32 v[92:93], v[92:93], v[92:93], v[94:95]
	v_mov_b32_e32 v74, v87
	v_mov_b32_e32 v75, v91
	v_pk_fma_f32 v[72:73], v[72:73], v[72:73], v[92:93]
	v_add_f32_e32 v70, v70, v71
	v_pk_fma_f32 v[72:73], v[74:75], v[74:75], v[72:73]
	ds_bpermute_b32 v74, v60, v102
	v_add_f32_e32 v70, v70, v72
	v_add_f32_e32 v70, v70, v73
	ds_bpermute_b32 v71, v60, v70
	ds_bpermute_b32 v98, v64, v69
	s_waitcnt lgkmcnt(2)
	v_add_f32_e32 v74, v102, v74
	ds_bpermute_b32 v75, v61, v74
	v_add_f32_e32 v72, v96, v97
	s_waitcnt lgkmcnt(2)
	v_add_f32_e32 v70, v70, v71
	ds_bpermute_b32 v71, v61, v70
	s_waitcnt lgkmcnt(2)
	v_add_f32_e32 v73, v69, v98
	ds_bpermute_b32 v69, v60, v72
	s_waitcnt lgkmcnt(2)
	v_add_f32_e32 v74, v74, v75
	ds_bpermute_b32 v75, v62, v74
	s_waitcnt lgkmcnt(2)
	v_add_f32_e32 v70, v70, v71
	ds_bpermute_b32 v71, v62, v70
	s_waitcnt lgkmcnt(2)
	v_add_f32_e32 v69, v72, v69
	ds_bpermute_b32 v72, v61, v69
	s_waitcnt lgkmcnt(2)
	v_add_f32_e32 v74, v74, v75
	ds_bpermute_b32 v75, v63, v74
	s_waitcnt lgkmcnt(2)
	v_add_f32_e32 v70, v70, v71
	ds_bpermute_b32 v71, v63, v70
	s_waitcnt lgkmcnt(2)
	v_add_f32_e32 v69, v69, v72
	ds_bpermute_b32 v72, v62, v69
	s_waitcnt lgkmcnt(2)
	v_add_f32_e32 v75, v74, v75
	ds_bpermute_b32 v92, v64, v75
	s_waitcnt lgkmcnt(2)
	v_add_f32_e32 v70, v70, v71
	ds_bpermute_b32 v71, v64, v70
	s_waitcnt lgkmcnt(2)
	v_add_f32_e32 v69, v69, v72
	ds_bpermute_b32 v72, v63, v69
	ds_bpermute_b32 v74, v65, v73
	s_waitcnt lgkmcnt(2)
	v_add_f32_e32 v70, v70, v71
	ds_bpermute_b32 v94, v65, v70
	v_add_f32_e32 v71, v75, v92
	s_waitcnt lgkmcnt(2)
	v_add_f32_e32 v69, v69, v72
	ds_bpermute_b32 v93, v64, v69
	ds_bpermute_b32 v72, v65, v71
	s_waitcnt lgkmcnt(2)
	v_add_f32_e32 v70, v70, v94
	v_fmamk_f32 v70, v70, 0x3a800000, v67
	v_mul_f32_e32 v75, 0x4b800000, v70
	v_cmp_gt_f32_e64 s[10:11], s22, v70
	s_waitcnt lgkmcnt(1)
	v_add_f32_e32 v69, v69, v93
	v_cndmask_b32_e64 v70, v70, v75, s[10:11]
	v_rsq_f32_e32 v75, v70
	ds_bpermute_b32 v70, v65, v69
	v_mul_f32_e32 v92, 0x45800000, v75
	v_cndmask_b32_e64 v92, v75, v92, s[10:11]
	v_pk_mul_f32 v[76:77], v[76:77], v[92:93] op_sel_hi:[1,0]
	v_pk_mul_f32 v[78:79], v[78:79], v[92:93] op_sel_hi:[1,0]
	v_cvt_pk_bf16_f32 v76, v76, v77
	v_cvt_pk_bf16_f32 v77, v78, v79
	global_store_dwordx2 v[58:59], v[76:77], off sc1
	v_pk_mul_f32 v[76:77], v[80:81], v[92:93] op_sel_hi:[1,0]
	v_pk_mul_f32 v[78:79], v[82:83], v[92:93] op_sel_hi:[1,0]
	v_cvt_pk_bf16_f32 v76, v76, v77
	v_cvt_pk_bf16_f32 v77, v78, v79
	global_store_dwordx2 v[58:59], v[76:77], off offset:512 sc1
	v_pk_mul_f32 v[76:77], v[84:85], v[92:93] op_sel_hi:[1,0]
	v_pk_mul_f32 v[78:79], v[86:87], v[92:93] op_sel_hi:[1,0]
	v_cvt_pk_bf16_f32 v76, v76, v77
	v_cvt_pk_bf16_f32 v77, v78, v79
	global_store_dwordx2 v[58:59], v[76:77], off offset:1024 sc1
	v_pk_mul_f32 v[76:77], v[88:89], v[92:93] op_sel_hi:[1,0]
	v_pk_mul_f32 v[78:79], v[90:91], v[92:93] op_sel_hi:[1,0]
	v_cvt_pk_bf16_f32 v76, v76, v77
	v_cvt_pk_bf16_f32 v77, v78, v79
	global_store_dwordx2 v[58:59], v[76:77], off offset:1536 sc1
	s_and_saveexec_b64 s[10:11], s[8:9]
	s_cbranch_execnz .Lrnp1_a391
	s_or_b64 exec, exec, s[10:11]
	s_and_saveexec_b64 s[8:9], s[4:5]
	s_cbranch_execnz .Lrnp1_a392

.Lrnp1_bt:
	s_or_b64 exec, exec, s[8:9]
	v_cmp_gt_i32_e64 s[6:7], s3, v182
	v_subrev_u32_e32 v113, s18, v182
	v_cmp_gt_i32_e64 s[4:5], s3, v113
	v_subrev_u32_e32 v113, s18, v113
	v_cmp_gt_i32_e64 s[8:9], s3, v113
	s_nop 1
	s_waitcnt vmcnt(15)
	v_pk_mul_f32 v[70:71], v[158:159], v[158:159]
	s_waitcnt vmcnt(14)
	v_pk_mul_f32 v[74:75], v[154:155], v[154:155]
	v_pk_mul_f32 v[72:73], v[160:161], v[160:161]
	v_pk_mul_f32 v[92:93], v[156:157], v[156:157]
	s_waitcnt vmcnt(13)
	v_pk_mul_f32 v[94:95], v[150:151], v[150:151]
	v_add_f32_e32 v69, v74, v75
	v_add_f32_e32 v110, v70, v71
	v_pk_mul_f32 v[96:97], v[152:153], v[152:153]
	s_waitcnt vmcnt(12)
	v_pk_mul_f32 v[98:99], v[146:147], v[146:147]
	v_add_f32_e32 v111, v94, v95
	v_add_f32_e32 v69, v69, v92
	v_add_f32_e32 v72, v110, v72
	v_pk_mul_f32 v[100:101], v[148:149], v[148:149]
	v_add_f32_e32 v112, v98, v99
	v_add_f32_e32 v92, v111, v96
	v_add_f32_e32 v69, v69, v93
	v_add_f32_e32 v72, v72, v73
	v_add_f32_e32 v96, v112, v100
	v_add_f32_e32 v73, v92, v97
	v_add_f32_e32 v69, v72, v69
	v_add_f32_e32 v92, v96, v101
	v_add_f32_e32 v69, v69, v73
	s_waitcnt vmcnt(11)
	v_pk_mul_f32 v[70:71], v[142:143], v[142:143]
	s_waitcnt vmcnt(9)
	v_pk_mul_f32 v[102:103], v[134:135], v[134:135]
	v_add_f32_e32 v69, v69, v92
	v_add_f32_e32 v70, v70, v71
	v_add_f32_e32 v71, v102, v103
	ds_bpermute_b32 v103, v60, v69
	v_pk_mul_f32 v[74:75], v[144:145], v[144:145]
	v_pk_mul_f32 v[94:95], v[138:139], v[138:139]
	v_pk_mul_f32 v[98:99], v[140:141], v[140:141]
	v_add_f32_e32 v94, v94, v95
	v_add_f32_e32 v70, v70, v74
	v_pk_mul_f32 v[104:105], v[136:137], v[136:137]
	v_add_f32_e32 v72, v94, v98
	v_add_f32_e32 v70, v70, v75
	s_waitcnt vmcnt(6)
	v_pk_mul_f32 v[74:75], v[122:123], v[122:123]
	s_waitcnt lgkmcnt(0)
	v_add_f32_e32 v69, v69, v103
	v_add_f32_e32 v72, v72, v99
	v_add_f32_e32 v71, v71, v104
	v_add_f32_e32 v74, v74, v75
	ds_bpermute_b32 v75, v61, v69
	v_pk_mul_f32 v[106:107], v[130:131], v[130:131]
	v_add_f32_e32 v70, v70, v72
	v_add_f32_e32 v71, v71, v105
	v_pk_mul_f32 v[108:109], v[132:133], v[132:133]
	v_add_f32_e32 v70, v70, v71
	v_add_f32_e32 v71, v106, v107
	v_add_f32_e32 v71, v71, v108
	v_add_f32_e32 v71, v71, v109
	v_add_f32_e32 v102, v70, v71
	v_pk_mul_f32 v[70:71], v[126:127], v[126:127]
	s_waitcnt lgkmcnt(0)
	v_add_f32_e32 v69, v69, v75
	v_add_f32_e32 v70, v70, v71
	ds_bpermute_b32 v71, v62, v69
	v_pk_mul_f32 v[72:73], v[128:129], v[128:129]
	v_pk_mul_f32 v[92:93], v[124:125], v[124:125]
	s_waitcnt vmcnt(5)
	v_pk_mul_f32 v[94:95], v[118:119], v[118:119]
	v_pk_mul_f32 v[96:97], v[120:121], v[120:121]
	s_waitcnt lgkmcnt(0)
	v_add_f32_e32 v69, v69, v71
	v_add_f32_e32 v74, v74, v92
	v_add_f32_e32 v70, v70, v72
	v_add_f32_e32 v72, v94, v95
	ds_bpermute_b32 v71, v63, v69
	v_add_f32_e32 v74, v74, v93
	v_add_f32_e32 v70, v70, v73
	v_add_f32_e32 v72, v72, v96
	s_waitcnt vmcnt(4)
	v_pk_mul_f32 v[98:99], v[114:115], v[114:115]
	v_add_f32_e32 v70, v70, v74
	v_add_f32_e32 v72, v72, v97
	v_pk_mul_f32 v[100:101], v[116:117], v[116:117]
	v_add_f32_e32 v96, v70, v72
	v_add_f32_e32 v70, v98, v99
	s_waitcnt vmcnt(3)
	v_mov_b32_e32 v92, v191
	s_waitcnt vmcnt(2)
	v_mov_b32_e32 v93, v195
	v_add_f32_e32 v70, v70, v100
	v_mov_b32_e32 v74, v190
	v_mov_b32_e32 v75, v194
	v_pk_mul_f32 v[92:93], v[92:93], v[92:93]
	v_add_f32_e32 v97, v70, v101
	s_waitcnt lgkmcnt(0)
	v_add_f32_e32 v69, v69, v71
	v_mov_b32_e32 v70, v192
	v_mov_b32_e32 v71, v196
	v_pk_fma_f32 v[74:75], v[74:75], v[74:75], v[92:93]
	s_waitcnt vmcnt(1)
	v_mov_b32_e32 v94, v199
	s_waitcnt vmcnt(0)
	v_mov_b32_e32 v95, v203
	v_mov_b32_e32 v72, v193
	v_mov_b32_e32 v73, v197
	v_pk_fma_f32 v[70:71], v[70:71], v[70:71], v[74:75]
	v_mov_b32_e32 v92, v198
	v_mov_b32_e32 v93, v202
	v_pk_mul_f32 v[94:95], v[94:95], v[94:95]
	v_pk_fma_f32 v[70:71], v[72:73], v[72:73], v[70:71]
	v_mov_b32_e32 v72, v200
	v_mov_b32_e32 v73, v204
	v_pk_fma_f32 v[92:93], v[92:93], v[92:93], v[94:95]
	v_mov_b32_e32 v74, v201
	v_mov_b32_e32 v75, v205
	v_pk_fma_f32 v[72:73], v[72:73], v[72:73], v[92:93]
	v_add_f32_e32 v70, v70, v71
	v_pk_fma_f32 v[72:73], v[74:75], v[74:75], v[72:73]
	ds_bpermute_b32 v74, v60, v102
	v_add_f32_e32 v70, v70, v72
	v_add_f32_e32 v70, v70, v73
	ds_bpermute_b32 v71, v60, v70
	ds_bpermute_b32 v98, v64, v69
	s_waitcnt lgkmcnt(2)
	v_add_f32_e32 v74, v102, v74
	ds_bpermute_b32 v75, v61, v74
	v_add_f32_e32 v72, v96, v97
	s_waitcnt lgkmcnt(2)
	v_add_f32_e32 v70, v70, v71
	ds_bpermute_b32 v71, v61, v70
	s_waitcnt lgkmcnt(2)
	v_add_f32_e32 v73, v69, v98
	ds_bpermute_b32 v69, v60, v72
	s_waitcnt lgkmcnt(2)
	v_add_f32_e32 v74, v74, v75
	ds_bpermute_b32 v75, v62, v74
	s_waitcnt lgkmcnt(2)
	v_add_f32_e32 v70, v70, v71
	ds_bpermute_b32 v71, v62, v70
	s_waitcnt lgkmcnt(2)
	v_add_f32_e32 v69, v72, v69
	ds_bpermute_b32 v72, v61, v69
	s_waitcnt lgkmcnt(2)
	v_add_f32_e32 v74, v74, v75
	ds_bpermute_b32 v75, v63, v74
	s_waitcnt lgkmcnt(2)
	v_add_f32_e32 v70, v70, v71
	ds_bpermute_b32 v71, v63, v70
	s_waitcnt lgkmcnt(2)
	v_add_f32_e32 v69, v69, v72
	ds_bpermute_b32 v72, v62, v69
	s_waitcnt lgkmcnt(2)
	v_add_f32_e32 v75, v74, v75
	ds_bpermute_b32 v92, v64, v75
	s_waitcnt lgkmcnt(2)
	v_add_f32_e32 v70, v70, v71
	ds_bpermute_b32 v71, v64, v70
	s_waitcnt lgkmcnt(2)
	v_add_f32_e32 v69, v69, v72
	ds_bpermute_b32 v72, v63, v69
	ds_bpermute_b32 v74, v65, v73
	s_waitcnt lgkmcnt(2)
	v_add_f32_e32 v70, v70, v71
	ds_bpermute_b32 v94, v65, v70
	v_add_f32_e32 v71, v75, v92
	s_waitcnt lgkmcnt(2)
	v_add_f32_e32 v69, v69, v72
	ds_bpermute_b32 v93, v64, v69
	ds_bpermute_b32 v72, v65, v71
	s_waitcnt lgkmcnt(2)
	v_add_f32_e32 v70, v70, v94
	v_fmamk_f32 v70, v70, 0x3a800000, v67
	v_mul_f32_e32 v75, 0x4b800000, v70
	v_cmp_gt_f32_e64 s[10:11], s22, v70
	s_waitcnt lgkmcnt(1)
	v_add_f32_e32 v69, v69, v93
	v_cndmask_b32_e64 v70, v70, v75, s[10:11]
	v_rsq_f32_e32 v75, v70
	ds_bpermute_b32 v70, v65, v69
	v_mul_f32_e32 v92, 0x45800000, v75
	v_cndmask_b32_e64 v92, v75, v92, s[10:11]
	v_pk_mul_f32 v[190:191], v[190:191], v[92:93] op_sel_hi:[1,0]
	v_pk_mul_f32 v[192:193], v[192:193], v[92:93] op_sel_hi:[1,0]
	v_cvt_pk_bf16_f32 v190, v190, v191
	v_cvt_pk_bf16_f32 v191, v192, v193
	global_store_dwordx2 v[172:173], v[190:191], off sc1
	v_pk_mul_f32 v[190:191], v[194:195], v[92:93] op_sel_hi:[1,0]
	v_pk_mul_f32 v[192:193], v[196:197], v[92:93] op_sel_hi:[1,0]
	v_cvt_pk_bf16_f32 v190, v190, v191
	v_cvt_pk_bf16_f32 v191, v192, v193
	global_store_dwordx2 v[172:173], v[190:191], off offset:512 sc1
	v_pk_mul_f32 v[190:191], v[198:199], v[92:93] op_sel_hi:[1,0]
	v_pk_mul_f32 v[192:193], v[200:201], v[92:93] op_sel_hi:[1,0]
	v_cvt_pk_bf16_f32 v190, v190, v191
	v_cvt_pk_bf16_f32 v191, v192, v193
	global_store_dwordx2 v[172:173], v[190:191], off offset:1024 sc1
	v_pk_mul_f32 v[190:191], v[202:203], v[92:93] op_sel_hi:[1,0]
	v_pk_mul_f32 v[192:193], v[204:205], v[92:93] op_sel_hi:[1,0]
	v_cvt_pk_bf16_f32 v190, v190, v191
	v_cvt_pk_bf16_f32 v191, v192, v193
	global_store_dwordx2 v[172:173], v[190:191], off offset:1536 sc1
	s_and_saveexec_b64 s[10:11], s[8:9]
	s_cbranch_execnz .Lrnp1_b391
	s_or_b64 exec, exec, s[10:11]
	s_and_saveexec_b64 s[8:9], s[4:5]
	s_cbranch_execnz .Lrnp1_b392

.Lrnp1_b391:
	v_add_f32_e32 v172, v73, v74
	v_fmamk_f32 v172, v172, 0x3a800000, v67
	v_mul_f32_e32 v173, 0x4b800000, v172
	v_cmp_gt_f32_e64 s[8:9], s22, v172
	v_lshlrev_b64 v[170:171], 11, v[170:171]
	s_nop 0
	v_cndmask_b32_e64 v172, v172, v173, s[8:9]
	v_rsq_f32_e32 v172, v172
	s_nop 0
	v_mul_f32_e32 v173, 0x45800000, v172
	v_cndmask_b32_e64 v172, v172, v173, s[8:9]
	v_pk_mul_f32 v[158:159], v[158:159], v[172:173] op_sel_hi:[1,0]
	v_pk_mul_f32 v[160:161], v[160:161], v[172:173] op_sel_hi:[1,0]
	v_pk_mul_f32 v[154:155], v[154:155], v[172:173] op_sel_hi:[1,0]
	v_pk_mul_f32 v[156:157], v[156:157], v[172:173] op_sel_hi:[1,0]
	v_pk_mul_f32 v[150:151], v[150:151], v[172:173] op_sel_hi:[1,0]
	v_pk_mul_f32 v[152:153], v[152:153], v[172:173] op_sel_hi:[1,0]
	v_pk_mul_f32 v[146:147], v[146:147], v[172:173] op_sel_hi:[1,0]
	v_pk_mul_f32 v[148:149], v[148:149], v[172:173] op_sel_hi:[1,0]
	v_cvt_pk_bf16_f32 v158, v158, v159
	v_cvt_pk_bf16_f32 v159, v160, v161
	v_lshl_add_u64 v[160:161], v[48:49], 0, v[170:171]
	v_cvt_pk_bf16_f32 v154, v154, v155
	v_cvt_pk_bf16_f32 v155, v156, v157
	v_cvt_pk_bf16_f32 v150, v150, v151
	v_cvt_pk_bf16_f32 v151, v152, v153
	v_cvt_pk_bf16_f32 v146, v146, v147
	v_cvt_pk_bf16_f32 v147, v148, v149
	global_store_dwordx2 v[160:161], v[158:159], off sc1
	global_store_dwordx2 v[160:161], v[154:155], off offset:512 sc1
	global_store_dwordx2 v[160:161], v[150:151], off offset:1024 sc1
	global_store_dwordx2 v[160:161], v[146:147], off offset:1536 sc1
	s_or_b64 exec, exec, s[10:11]
	s_and_saveexec_b64 s[8:9], s[4:5]
	s_cbranch_execz .Lrnp1_b390
.Lrnp1_b392:
	s_waitcnt lgkmcnt(1)
	v_add_f32_e32 v146, v71, v72
	v_fmamk_f32 v146, v146, 0x3a800000, v67
	v_mul_f32_e32 v147, 0x4b800000, v146
	v_cmp_gt_f32_e64 s[4:5], s22, v146
	s_nop 1
	v_cndmask_b32_e64 v146, v146, v147, s[4:5]
	v_rsq_f32_e32 v148, v146
	v_lshlrev_b64 v[146:147], 11, v[168:169]
	v_mul_f32_e32 v149, 0x45800000, v148
	v_cndmask_b32_e64 v148, v148, v149, s[4:5]
	v_pk_mul_f32 v[142:143], v[142:143], v[148:149] op_sel_hi:[1,0]
	v_pk_mul_f32 v[144:145], v[144:145], v[148:149] op_sel_hi:[1,0]
	v_pk_mul_f32 v[138:139], v[138:139], v[148:149] op_sel_hi:[1,0]
	v_pk_mul_f32 v[140:141], v[140:141], v[148:149] op_sel_hi:[1,0]
	v_pk_mul_f32 v[134:135], v[134:135], v[148:149] op_sel_hi:[1,0]
	v_pk_mul_f32 v[136:137], v[136:137], v[148:149] op_sel_hi:[1,0]
	v_pk_mul_f32 v[130:131], v[130:131], v[148:149] op_sel_hi:[1,0]
	v_pk_mul_f32 v[132:133], v[132:133], v[148:149] op_sel_hi:[1,0]
	v_cvt_pk_bf16_f32 v142, v142, v143
	v_cvt_pk_bf16_f32 v143, v144, v145
	v_lshl_add_u64 v[144:145], v[48:49], 0, v[146:147]
	v_cvt_pk_bf16_f32 v138, v138, v139
	v_cvt_pk_bf16_f32 v139, v140, v141
	v_cvt_pk_bf16_f32 v134, v134, v135
	v_cvt_pk_bf16_f32 v135, v136, v137
	v_cvt_pk_bf16_f32 v130, v130, v131
	v_cvt_pk_bf16_f32 v131, v132, v133
	global_store_dwordx2 v[144:145], v[142:143], off sc1
	global_store_dwordx2 v[144:145], v[138:139], off offset:512 sc1
	global_store_dwordx2 v[144:145], v[134:135], off offset:1024 sc1
	global_store_dwordx2 v[144:145], v[130:131], off offset:1536 sc1
	s_or_b64 exec, exec, s[8:9]
	s_and_saveexec_b64 s[8:9], s[6:7]
	s_cbranch_execz .Lrnp1_bc
.Lrnp1_b393:
	s_waitcnt lgkmcnt(0)
	v_add_f32_e32 v130, v69, v70
	v_fmamk_f32 v130, v130, 0x3a800000, v67
	v_mul_f32_e32 v131, 0x4b800000, v130
	v_cmp_gt_f32_e64 s[4:5], s22, v130
	s_nop 1
	v_cndmask_b32_e64 v130, v130, v131, s[4:5]
	v_rsq_f32_e32 v132, v130
	v_lshlrev_b64 v[130:131], 11, v[166:167]
	v_mul_f32_e32 v133, 0x45800000, v132
	v_cndmask_b32_e64 v132, v132, v133, s[4:5]
	v_pk_mul_f32 v[126:127], v[126:127], v[132:133] op_sel_hi:[1,0]
	v_pk_mul_f32 v[128:129], v[128:129], v[132:133] op_sel_hi:[1,0]
	v_pk_mul_f32 v[122:123], v[122:123], v[132:133] op_sel_hi:[1,0]
	v_pk_mul_f32 v[124:125], v[124:125], v[132:133] op_sel_hi:[1,0]
	v_pk_mul_f32 v[118:119], v[118:119], v[132:133] op_sel_hi:[1,0]
	v_pk_mul_f32 v[120:121], v[120:121], v[132:133] op_sel_hi:[1,0]
	v_pk_mul_f32 v[114:115], v[114:115], v[132:133] op_sel_hi:[1,0]
	v_pk_mul_f32 v[116:117], v[116:117], v[132:133] op_sel_hi:[1,0]
	v_cvt_pk_bf16_f32 v126, v126, v127
	v_cvt_pk_bf16_f32 v127, v128, v129
	v_lshl_add_u64 v[128:129], v[48:49], 0, v[130:131]
	v_cvt_pk_bf16_f32 v122, v122, v123
	v_cvt_pk_bf16_f32 v123, v124, v125
	v_cvt_pk_bf16_f32 v118, v118, v119
	v_cvt_pk_bf16_f32 v119, v120, v121
	v_cvt_pk_bf16_f32 v114, v114, v115
	v_cvt_pk_bf16_f32 v115, v116, v117
	global_store_dwordx2 v[128:129], v[126:127], off sc1
	global_store_dwordx2 v[128:129], v[122:123], off offset:512 sc1
	global_store_dwordx2 v[128:129], v[118:119], off offset:1024 sc1
	global_store_dwordx2 v[128:129], v[114:115], off offset:1536 sc1
	s_branch .Lrnp1_bc
.Lrnp1_bc:
	s_or_b64 exec, exec, s[8:9]
	v_add_u32_e32 v58, s18, v182
	v_cmp_lt_i32_e64 s[4:5], s23, v58
	s_or_b64 s[16:17], s[4:5], s[16:17]
	v_add_u32_e32 v66, s19, v180
	s_andn2_b64 exec, exec, s[16:17]
	s_cbranch_execz .LBB0_394
	s_branch .LBB0_388
.Lrnp1_orig:
	s_waitcnt vmcnt(15)
	v_pk_mul_f32 v[70:71], v[44:45], v[44:45]
	s_waitcnt vmcnt(14)
	v_pk_mul_f32 v[74:75], v[40:41], v[40:41]
	v_pk_mul_f32 v[72:73], v[46:47], v[46:47]
	v_pk_mul_f32 v[92:93], v[42:43], v[42:43]
	s_waitcnt vmcnt(13)
	v_pk_mul_f32 v[94:95], v[36:37], v[36:37]
	v_add_f32_e32 v69, v74, v75
	v_add_f32_e32 v110, v70, v71
	v_pk_mul_f32 v[96:97], v[38:39], v[38:39]
	s_waitcnt vmcnt(12)
	v_pk_mul_f32 v[98:99], v[32:33], v[32:33]
	v_add_f32_e32 v111, v94, v95
	v_add_f32_e32 v69, v69, v92
	v_add_f32_e32 v72, v110, v72
	v_pk_mul_f32 v[100:101], v[34:35], v[34:35]
	v_add_f32_e32 v112, v98, v99
	v_add_f32_e32 v92, v111, v96
	v_add_f32_e32 v69, v69, v93
	v_add_f32_e32 v72, v72, v73
	v_add_f32_e32 v96, v112, v100
	v_add_f32_e32 v73, v92, v97
	v_add_f32_e32 v69, v72, v69
	v_add_f32_e32 v92, v96, v101
	v_add_f32_e32 v69, v69, v73
	s_waitcnt vmcnt(11)
	v_pk_mul_f32 v[70:71], v[28:29], v[28:29]
	s_waitcnt vmcnt(9)
	v_pk_mul_f32 v[102:103], v[20:21], v[20:21]
	v_add_f32_e32 v69, v69, v92
	v_add_f32_e32 v70, v70, v71
	v_add_f32_e32 v71, v102, v103
	ds_bpermute_b32 v103, v60, v69
	v_pk_mul_f32 v[74:75], v[30:31], v[30:31]
	v_pk_mul_f32 v[94:95], v[24:25], v[24:25]
	v_pk_mul_f32 v[98:99], v[26:27], v[26:27]
	v_add_f32_e32 v94, v94, v95
	v_add_f32_e32 v70, v70, v74
	v_pk_mul_f32 v[104:105], v[22:23], v[22:23]
	v_add_f32_e32 v72, v94, v98
	v_add_f32_e32 v70, v70, v75
	s_waitcnt vmcnt(6)
	v_pk_mul_f32 v[74:75], v[8:9], v[8:9]
	s_waitcnt lgkmcnt(0)
	v_add_f32_e32 v69, v69, v103
	v_add_f32_e32 v72, v72, v99
	v_add_f32_e32 v71, v71, v104
	v_add_f32_e32 v74, v74, v75
	ds_bpermute_b32 v75, v61, v69
	v_pk_mul_f32 v[106:107], v[16:17], v[16:17]
	v_add_f32_e32 v70, v70, v72
	v_add_f32_e32 v71, v71, v105
	v_pk_mul_f32 v[108:109], v[18:19], v[18:19]
	v_add_f32_e32 v70, v70, v71
	v_add_f32_e32 v71, v106, v107
	v_add_f32_e32 v71, v71, v108
	v_add_f32_e32 v71, v71, v109
	v_add_f32_e32 v102, v70, v71
	v_pk_mul_f32 v[70:71], v[12:13], v[12:13]
	s_waitcnt lgkmcnt(0)
	v_add_f32_e32 v69, v69, v75
	v_add_f32_e32 v70, v70, v71
	ds_bpermute_b32 v71, v62, v69
	v_pk_mul_f32 v[72:73], v[14:15], v[14:15]
	v_pk_mul_f32 v[92:93], v[10:11], v[10:11]
	s_waitcnt vmcnt(5)
	v_pk_mul_f32 v[94:95], v[4:5], v[4:5]
	v_pk_mul_f32 v[96:97], v[6:7], v[6:7]
	s_waitcnt lgkmcnt(0)
	v_add_f32_e32 v69, v69, v71
	v_add_f32_e32 v74, v74, v92
	v_add_f32_e32 v70, v70, v72
	v_add_f32_e32 v72, v94, v95
	ds_bpermute_b32 v71, v63, v69
	v_add_f32_e32 v74, v74, v93
	v_add_f32_e32 v70, v70, v73
	v_add_f32_e32 v72, v72, v96
	s_waitcnt vmcnt(4)
	v_pk_mul_f32 v[98:99], v[0:1], v[0:1]
	v_add_f32_e32 v70, v70, v74
	v_add_f32_e32 v72, v72, v97
	v_pk_mul_f32 v[100:101], v[2:3], v[2:3]
	v_add_f32_e32 v96, v70, v72
	v_add_f32_e32 v70, v98, v99
	s_waitcnt vmcnt(3)
	v_mov_b32_e32 v92, v77
	s_waitcnt vmcnt(2)
	v_mov_b32_e32 v93, v81
	v_add_f32_e32 v70, v70, v100
	v_mov_b32_e32 v74, v76
	v_mov_b32_e32 v75, v80
	v_pk_mul_f32 v[92:93], v[92:93], v[92:93]
	v_add_f32_e32 v97, v70, v101
	s_waitcnt lgkmcnt(0)
	v_add_f32_e32 v69, v69, v71
	v_mov_b32_e32 v70, v78
	v_mov_b32_e32 v71, v82
	v_pk_fma_f32 v[74:75], v[74:75], v[74:75], v[92:93]
	s_waitcnt vmcnt(1)
	v_mov_b32_e32 v94, v85
	s_waitcnt vmcnt(0)
	v_mov_b32_e32 v95, v89
	v_mov_b32_e32 v72, v79
	v_mov_b32_e32 v73, v83
	v_pk_fma_f32 v[70:71], v[70:71], v[70:71], v[74:75]
	v_mov_b32_e32 v92, v84
	v_mov_b32_e32 v93, v88
	v_pk_mul_f32 v[94:95], v[94:95], v[94:95]
	v_pk_fma_f32 v[70:71], v[72:73], v[72:73], v[70:71]
	v_mov_b32_e32 v72, v86
	v_mov_b32_e32 v73, v90
	v_pk_fma_f32 v[92:93], v[92:93], v[92:93], v[94:95]
	v_mov_b32_e32 v74, v87
	v_mov_b32_e32 v75, v91
	v_pk_fma_f32 v[72:73], v[72:73], v[72:73], v[92:93]
	v_add_f32_e32 v70, v70, v71
	v_pk_fma_f32 v[72:73], v[74:75], v[74:75], v[72:73]
	ds_bpermute_b32 v74, v60, v102
	v_add_f32_e32 v70, v70, v72
	v_add_f32_e32 v70, v70, v73
	ds_bpermute_b32 v71, v60, v70
	ds_bpermute_b32 v98, v64, v69
	s_waitcnt lgkmcnt(2)
	v_add_f32_e32 v74, v102, v74
	ds_bpermute_b32 v75, v61, v74
	v_add_f32_e32 v72, v96, v97
	s_waitcnt lgkmcnt(2)
	v_add_f32_e32 v70, v70, v71
	ds_bpermute_b32 v71, v61, v70
	s_waitcnt lgkmcnt(2)
	v_add_f32_e32 v73, v69, v98
	ds_bpermute_b32 v69, v60, v72
	s_waitcnt lgkmcnt(2)
	v_add_f32_e32 v74, v74, v75
	ds_bpermute_b32 v75, v62, v74
	s_waitcnt lgkmcnt(2)
	v_add_f32_e32 v70, v70, v71
	ds_bpermute_b32 v71, v62, v70
	s_waitcnt lgkmcnt(2)
	v_add_f32_e32 v69, v72, v69
	ds_bpermute_b32 v72, v61, v69
	s_waitcnt lgkmcnt(2)
	v_add_f32_e32 v74, v74, v75
	ds_bpermute_b32 v75, v63, v74
	s_waitcnt lgkmcnt(2)
	v_add_f32_e32 v70, v70, v71
	ds_bpermute_b32 v71, v63, v70
	s_waitcnt lgkmcnt(2)
	v_add_f32_e32 v69, v69, v72
	ds_bpermute_b32 v72, v62, v69
	s_waitcnt lgkmcnt(2)
	v_add_f32_e32 v75, v74, v75
	ds_bpermute_b32 v92, v64, v75
	s_waitcnt lgkmcnt(2)
	v_add_f32_e32 v70, v70, v71
	ds_bpermute_b32 v71, v64, v70
	s_waitcnt lgkmcnt(2)
	v_add_f32_e32 v69, v69, v72
	ds_bpermute_b32 v72, v63, v69
	ds_bpermute_b32 v74, v65, v73
	s_waitcnt lgkmcnt(2)
	v_add_f32_e32 v70, v70, v71
	ds_bpermute_b32 v94, v65, v70
	v_add_f32_e32 v71, v75, v92
	s_waitcnt lgkmcnt(2)
	v_add_f32_e32 v69, v69, v72
	ds_bpermute_b32 v93, v64, v69
	ds_bpermute_b32 v72, v65, v71
	s_waitcnt lgkmcnt(2)
	v_add_f32_e32 v70, v70, v94
	v_fmamk_f32 v70, v70, 0x3a800000, v67
	v_mul_f32_e32 v75, 0x4b800000, v70
	v_cmp_gt_f32_e64 s[10:11], s22, v70
	s_waitcnt lgkmcnt(1)
	v_add_f32_e32 v69, v69, v93
	v_cndmask_b32_e64 v70, v70, v75, s[10:11]
	v_rsq_f32_e32 v75, v70
	ds_bpermute_b32 v70, v65, v69
	v_mul_f32_e32 v92, 0x45800000, v75
	v_cndmask_b32_e64 v92, v75, v92, s[10:11]
	v_pk_mul_f32 v[76:77], v[76:77], v[92:93] op_sel_hi:[1,0]
	v_pk_mul_f32 v[78:79], v[78:79], v[92:93] op_sel_hi:[1,0]
	v_cvt_pk_bf16_f32 v76, v76, v77
	v_cvt_pk_bf16_f32 v77, v78, v79
	global_store_dwordx2 v[58:59], v[76:77], off sc1
	v_pk_mul_f32 v[76:77], v[80:81], v[92:93] op_sel_hi:[1,0]
	v_pk_mul_f32 v[78:79], v[82:83], v[92:93] op_sel_hi:[1,0]
	v_cvt_pk_bf16_f32 v76, v76, v77
	v_cvt_pk_bf16_f32 v77, v78, v79
	global_store_dwordx2 v[58:59], v[76:77], off offset:512 sc1
	v_pk_mul_f32 v[76:77], v[84:85], v[92:93] op_sel_hi:[1,0]
	v_pk_mul_f32 v[78:79], v[86:87], v[92:93] op_sel_hi:[1,0]
	v_cvt_pk_bf16_f32 v76, v76, v77
	v_cvt_pk_bf16_f32 v77, v78, v79
	global_store_dwordx2 v[58:59], v[76:77], off offset:1024 sc1
	v_pk_mul_f32 v[76:77], v[88:89], v[92:93] op_sel_hi:[1,0]
	v_pk_mul_f32 v[78:79], v[90:91], v[92:93] op_sel_hi:[1,0]
	v_cvt_pk_bf16_f32 v76, v76, v77
	v_cvt_pk_bf16_f32 v77, v78, v79
	global_store_dwordx2 v[58:59], v[76:77], off offset:1536 sc1
	s_and_saveexec_b64 s[10:11], s[8:9]
	s_cbranch_execnz .LBB0_391
	s_or_b64 exec, exec, s[10:11]
	s_and_saveexec_b64 s[8:9], s[4:5]
	s_cbranch_execnz .LBB0_392

.LBB0_868:
	v_add_u32_e32 v0, s16, v58
	v_cmp_gt_i32_e64 s[6:7], s3, v0
	v_lshrrev_b32_e32 v69, 3, v58
	v_and_b32_e32 v59, 0x700, v66
	v_cndmask_b32_e64 v1, v58, v0, s[6:7]
	v_lshlrev_b32_e32 v2, 5, v1
	v_lshrrev_b32_e32 v3, 3, v1
	v_and_b32_e32 v2, 0x700, v2
	v_and_b32_e32 v3, 0xf8, v3
	v_and_b32_e32 v4, 0xfffff807, v1
	v_or3_b32 v2, v2, v4, v3
	v_cndmask_b32_e32 v56, v1, v2, vcc
	v_add_u32_e32 v2, s16, v0
	v_cmp_gt_i32_e64 s[0:1], s3, v2
	v_ashrrev_i32_e32 v57, 31, v56
	v_add_u32_e32 v68, s16, v2
	v_cndmask_b32_e64 v3, v58, v2, s[0:1]
	v_lshlrev_b32_e32 v0, 5, v3
	v_and_b32_e32 v4, 0x700, v0
	v_lshlrev_b64 v[0:1], 12, v[56:57]
	v_lshl_add_u64 v[0:1], v[50:51], 0, v[0:1]
	v_lshrrev_b32_e32 v5, 3, v3
	global_load_dwordx4 v[44:47], v[0:1], off
	global_load_dwordx4 v[40:43], v[0:1], off offset:1024
	v_and_b32_e32 v5, 0xf8, v5
	v_and_b32_e32 v6, 0xfffff807, v3
	global_load_dwordx4 v[36:39], v[0:1], off offset:2048
	global_load_dwordx4 v[32:35], v[0:1], off offset:3072
	v_or3_b32 v0, v4, v6, v5
	v_cndmask_b32_e32 v54, v3, v0, vcc
	v_ashrrev_i32_e32 v55, 31, v54
	v_lshlrev_b64 v[0:1], 12, v[54:55]
	v_lshl_add_u64 v[0:1], v[50:51], 0, v[0:1]
	v_cmp_gt_i32_e64 s[4:5], s3, v68
	global_load_dwordx4 v[28:31], v[0:1], off
	global_load_dwordx4 v[24:27], v[0:1], off offset:1024
	global_load_dwordx4 v[20:23], v[0:1], off offset:2048
	global_load_dwordx4 v[16:19], v[0:1], off offset:3072
	v_cndmask_b32_e64 v0, v58, v68, s[4:5]
	v_lshlrev_b32_e32 v1, 5, v0
	v_lshrrev_b32_e32 v2, 3, v0
	v_and_b32_e32 v3, 0xfffff807, v0
	v_and_b32_e32 v1, 0x700, v1
	v_and_b32_e32 v2, 0xf8, v2
	v_or3_b32 v1, v1, v3, v2
	v_cndmask_b32_e32 v52, v0, v1, vcc
	v_ashrrev_i32_e32 v53, 31, v52
	v_lshlrev_b64 v[0:1], 12, v[52:53]
	v_lshl_add_u64 v[0:1], v[50:51], 0, v[0:1]
	global_load_dwordx4 v[12:15], v[0:1], off
	global_load_dwordx4 v[8:11], v[0:1], off offset:1024
	global_load_dwordx4 v[4:7], v[0:1], off offset:2048
	s_nop 0
	global_load_dwordx4 v[0:3], v[0:1], off offset:3072
	s_waitcnt lgkmcnt(0)
	v_and_b32_e32 v70, 0xfffff807, v58
	v_and_b32_e32 v69, 0xf8, v69
	v_or3_b32 v59, v59, v70, v69
	v_cndmask_b32_e32 v58, v58, v59, vcc
	v_ashrrev_i32_e32 v59, 31, v58
	v_lshlrev_b64 v[70:71], 12, v[58:59]
	v_lshl_add_u64 v[70:71], v[50:51], 0, v[70:71]
	global_load_dwordx4 v[76:79], v[70:71], off
	global_load_dwordx4 v[80:83], v[70:71], off offset:1024
	global_load_dwordx4 v[84:87], v[70:71], off offset:2048
	global_load_dwordx4 v[88:91], v[70:71], off offset:3072
	v_lshlrev_b64 v[58:59], 11, v[58:59]
	v_lshl_add_u64 v[58:59], v[48:49], 0, v[58:59]
	v_add_u32_e32 v172, s16, v68
	v_add_u32_e32 v180, s17, v66
	v_cmp_ge_i32_e64 s[8:9], s19, v172
	s_nop 1
	s_and_b64 s[8:9], s[8:9], exec
	s_cbranch_scc0 .Lrnp2_orig
	v_add_u32_e32 v114, s16, v172
	v_cmp_gt_i32_e64 s[8:9], s3, v114
	v_lshrrev_b32_e32 v183, 3, v172
	v_and_b32_e32 v173, 0x700, v180
	v_cndmask_b32_e64 v115, v172, v114, s[8:9]
	v_lshlrev_b32_e32 v116, 5, v115
	v_lshrrev_b32_e32 v117, 3, v115
	v_and_b32_e32 v116, 0x700, v116
	v_and_b32_e32 v117, 0xf8, v117
	v_and_b32_e32 v118, 0xfffff807, v115
	v_or3_b32 v116, v116, v118, v117
	v_cndmask_b32_e32 v170, v115, v116, vcc
	v_add_u32_e32 v116, s16, v114
	v_cmp_gt_i32_e64 s[8:9], s3, v116
	v_ashrrev_i32_e32 v171, 31, v170
	v_add_u32_e32 v182, s16, v116
	v_cndmask_b32_e64 v117, v172, v116, s[8:9]
	v_lshlrev_b32_e32 v114, 5, v117
	v_and_b32_e32 v118, 0x700, v114
	v_lshlrev_b64 v[114:115], 12, v[170:171]
	v_lshl_add_u64 v[114:115], v[50:51], 0, v[114:115]
	v_lshrrev_b32_e32 v119, 3, v117
	global_load_dwordx4 v[158:161], v[114:115], off
	global_load_dwordx4 v[154:157], v[114:115], off offset:1024
	v_and_b32_e32 v119, 0xf8, v119
	v_and_b32_e32 v120, 0xfffff807, v117
	global_load_dwordx4 v[150:153], v[114:115], off offset:2048
	global_load_dwordx4 v[146:149], v[114:115], off offset:3072
	v_or3_b32 v114, v118, v120, v119
	v_cndmask_b32_e32 v168, v117, v114, vcc
	v_ashrrev_i32_e32 v169, 31, v168
	v_lshlrev_b64 v[114:115], 12, v[168:169]
	v_lshl_add_u64 v[114:115], v[50:51], 0, v[114:115]
	v_cmp_gt_i32_e64 s[8:9], s3, v182
	global_load_dwordx4 v[142:145], v[114:115], off
	global_load_dwordx4 v[138:141], v[114:115], off offset:1024
	global_load_dwordx4 v[134:137], v[114:115], off offset:2048
	global_load_dwordx4 v[130:133], v[114:115], off offset:3072
	v_cndmask_b32_e64 v114, v172, v182, s[8:9]
	v_lshlrev_b32_e32 v115, 5, v114
	v_lshrrev_b32_e32 v116, 3, v114
	v_and_b32_e32 v117, 0xfffff807, v114
	v_and_b32_e32 v115, 0x700, v115
	v_and_b32_e32 v116, 0xf8, v116
	v_or3_b32 v115, v115, v117, v116
	v_cndmask_b32_e32 v166, v114, v115, vcc
	v_ashrrev_i32_e32 v167, 31, v166
	v_lshlrev_b64 v[114:115], 12, v[166:167]
	v_lshl_add_u64 v[114:115], v[50:51], 0, v[114:115]
	global_load_dwordx4 v[126:129], v[114:115], off
	global_load_dwordx4 v[122:125], v[114:115], off offset:1024
	global_load_dwordx4 v[118:121], v[114:115], off offset:2048
	s_nop 0
	global_load_dwordx4 v[114:117], v[114:115], off offset:3072
	s_waitcnt lgkmcnt(0)
	v_and_b32_e32 v184, 0xfffff807, v172
	v_and_b32_e32 v183, 0xf8, v183
	v_or3_b32 v173, v173, v184, v183
	v_cndmask_b32_e32 v172, v172, v173, vcc
	v_ashrrev_i32_e32 v173, 31, v172
	v_lshlrev_b64 v[184:185], 12, v[172:173]
	v_lshl_add_u64 v[184:185], v[50:51], 0, v[184:185]
	global_load_dwordx4 v[190:193], v[184:185], off
	global_load_dwordx4 v[194:197], v[184:185], off offset:1024
	global_load_dwordx4 v[198:201], v[184:185], off offset:2048
	global_load_dwordx4 v[202:205], v[184:185], off offset:3072
	v_lshlrev_b64 v[172:173], 11, v[172:173]
	v_lshl_add_u64 v[172:173], v[48:49], 0, v[172:173]
	s_waitcnt vmcnt(31)
	v_pk_mul_f32 v[70:71], v[44:45], v[44:45]
	s_waitcnt vmcnt(30)
	v_pk_mul_f32 v[74:75], v[40:41], v[40:41]
	v_pk_mul_f32 v[72:73], v[46:47], v[46:47]
	v_pk_mul_f32 v[92:93], v[42:43], v[42:43]
	s_waitcnt vmcnt(29)
	v_pk_mul_f32 v[94:95], v[36:37], v[36:37]
	v_add_f32_e32 v69, v74, v75
	v_add_f32_e32 v110, v70, v71
	v_pk_mul_f32 v[96:97], v[38:39], v[38:39]
	s_waitcnt vmcnt(28)
	v_pk_mul_f32 v[98:99], v[32:33], v[32:33]
	v_add_f32_e32 v111, v94, v95
	v_add_f32_e32 v69, v69, v92
	v_add_f32_e32 v72, v110, v72
	v_pk_mul_f32 v[100:101], v[34:35], v[34:35]
	v_add_f32_e32 v112, v98, v99
	v_add_f32_e32 v92, v111, v96
	v_add_f32_e32 v69, v69, v93
	v_add_f32_e32 v72, v72, v73
	v_add_f32_e32 v96, v112, v100
	v_add_f32_e32 v73, v92, v97
	v_add_f32_e32 v69, v72, v69
	v_add_f32_e32 v92, v96, v101
	v_add_f32_e32 v69, v69, v73
	s_waitcnt vmcnt(27)
	v_pk_mul_f32 v[70:71], v[28:29], v[28:29]
	s_waitcnt vmcnt(25)
	v_pk_mul_f32 v[102:103], v[20:21], v[20:21]
	v_add_f32_e32 v69, v69, v92
	v_add_f32_e32 v70, v70, v71
	v_add_f32_e32 v71, v102, v103
	ds_bpermute_b32 v103, v60, v69
	v_pk_mul_f32 v[74:75], v[30:31], v[30:31]
	v_pk_mul_f32 v[94:95], v[24:25], v[24:25]
	v_pk_mul_f32 v[98:99], v[26:27], v[26:27]
	v_add_f32_e32 v94, v94, v95
	v_add_f32_e32 v70, v70, v74
	v_pk_mul_f32 v[104:105], v[22:23], v[22:23]
	v_add_f32_e32 v72, v94, v98
	v_add_f32_e32 v70, v70, v75
	s_waitcnt vmcnt(22)
	v_pk_mul_f32 v[74:75], v[8:9], v[8:9]
	s_waitcnt lgkmcnt(0)
	v_add_f32_e32 v69, v69, v103
	v_add_f32_e32 v72, v72, v99
	v_add_f32_e32 v71, v71, v104
	v_add_f32_e32 v74, v74, v75
	ds_bpermute_b32 v75, v61, v69
	v_pk_mul_f32 v[106:107], v[16:17], v[16:17]
	v_add_f32_e32 v70, v70, v72
	v_add_f32_e32 v71, v71, v105
	v_pk_mul_f32 v[108:109], v[18:19], v[18:19]
	v_add_f32_e32 v70, v70, v71
	v_add_f32_e32 v71, v106, v107
	v_add_f32_e32 v71, v71, v108
	v_add_f32_e32 v71, v71, v109
	v_add_f32_e32 v102, v70, v71
	v_pk_mul_f32 v[70:71], v[12:13], v[12:13]
	s_waitcnt lgkmcnt(0)
	v_add_f32_e32 v69, v69, v75
	v_add_f32_e32 v70, v70, v71
	ds_bpermute_b32 v71, v62, v69
	v_pk_mul_f32 v[72:73], v[14:15], v[14:15]
	v_pk_mul_f32 v[92:93], v[10:11], v[10:11]
	s_waitcnt vmcnt(21)
	v_pk_mul_f32 v[94:95], v[4:5], v[4:5]
	v_pk_mul_f32 v[96:97], v[6:7], v[6:7]
	s_waitcnt lgkmcnt(0)
	v_add_f32_e32 v69, v69, v71
	v_add_f32_e32 v74, v74, v92
	v_add_f32_e32 v70, v70, v72
	v_add_f32_e32 v72, v94, v95
	ds_bpermute_b32 v71, v63, v69
	v_add_f32_e32 v74, v74, v93
	v_add_f32_e32 v70, v70, v73
	v_add_f32_e32 v72, v72, v96
	s_waitcnt vmcnt(20)
	v_pk_mul_f32 v[98:99], v[0:1], v[0:1]
	v_add_f32_e32 v70, v70, v74
	v_add_f32_e32 v72, v72, v97
	v_pk_mul_f32 v[100:101], v[2:3], v[2:3]
	v_add_f32_e32 v96, v70, v72
	v_add_f32_e32 v70, v98, v99
	s_waitcnt vmcnt(19)
	v_mov_b32_e32 v92, v77
	s_waitcnt vmcnt(18)
	v_mov_b32_e32 v93, v81
	v_add_f32_e32 v70, v70, v100
	v_mov_b32_e32 v74, v76
	v_mov_b32_e32 v75, v80
	v_pk_mul_f32 v[92:93], v[92:93], v[92:93]
	v_add_f32_e32 v97, v70, v101
	s_waitcnt lgkmcnt(0)
	v_add_f32_e32 v69, v69, v71
	v_mov_b32_e32 v70, v78
	v_mov_b32_e32 v71, v82
	v_pk_fma_f32 v[74:75], v[74:75], v[74:75], v[92:93]
	s_waitcnt vmcnt(17)
	v_mov_b32_e32 v94, v85
	s_waitcnt vmcnt(16)
	v_mov_b32_e32 v95, v89
	v_mov_b32_e32 v72, v79
	v_mov_b32_e32 v73, v83
	v_pk_fma_f32 v[70:71], v[70:71], v[70:71], v[74:75]
	v_mov_b32_e32 v92, v84
	v_mov_b32_e32 v93, v88
	v_pk_mul_f32 v[94:95], v[94:95], v[94:95]
	v_pk_fma_f32 v[70:71], v[72:73], v[72:73], v[70:71]
	v_mov_b32_e32 v72, v86
	v_mov_b32_e32 v73, v90
	v_pk_fma_f32 v[92:93], v[92:93], v[92:93], v[94:95]
	v_mov_b32_e32 v74, v87
	v_mov_b32_e32 v75, v91
	v_pk_fma_f32 v[72:73], v[72:73], v[72:73], v[92:93]
	v_add_f32_e32 v70, v70, v71
	v_pk_fma_f32 v[72:73], v[74:75], v[74:75], v[72:73]
	ds_bpermute_b32 v74, v60, v102
	v_add_f32_e32 v70, v70, v72
	v_add_f32_e32 v70, v70, v73
	ds_bpermute_b32 v71, v60, v70
	ds_bpermute_b32 v98, v64, v69
	s_waitcnt lgkmcnt(2)
	v_add_f32_e32 v74, v102, v74
	ds_bpermute_b32 v75, v61, v74
	v_add_f32_e32 v72, v96, v97
	s_waitcnt lgkmcnt(2)
	v_add_f32_e32 v70, v70, v71
	ds_bpermute_b32 v71, v61, v70
	s_waitcnt lgkmcnt(2)
	v_add_f32_e32 v73, v69, v98
	ds_bpermute_b32 v69, v60, v72
	s_waitcnt lgkmcnt(2)
	v_add_f32_e32 v74, v74, v75
	ds_bpermute_b32 v75, v62, v74
	s_waitcnt lgkmcnt(2)
	v_add_f32_e32 v70, v70, v71
	ds_bpermute_b32 v71, v62, v70
	s_waitcnt lgkmcnt(2)
	v_add_f32_e32 v69, v72, v69
	ds_bpermute_b32 v72, v61, v69
	s_waitcnt lgkmcnt(2)
	v_add_f32_e32 v74, v74, v75
	ds_bpermute_b32 v75, v63, v74
	s_waitcnt lgkmcnt(2)
	v_add_f32_e32 v70, v70, v71
	ds_bpermute_b32 v71, v63, v70
	s_waitcnt lgkmcnt(2)
	v_add_f32_e32 v69, v69, v72
	ds_bpermute_b32 v72, v62, v69
	s_waitcnt lgkmcnt(2)
	v_add_f32_e32 v75, v74, v75
	ds_bpermute_b32 v92, v64, v75
	s_waitcnt lgkmcnt(2)
	v_add_f32_e32 v70, v70, v71
	ds_bpermute_b32 v71, v64, v70
	s_waitcnt lgkmcnt(2)
	v_add_f32_e32 v69, v69, v72
	ds_bpermute_b32 v72, v63, v69
	ds_bpermute_b32 v74, v65, v73
	s_waitcnt lgkmcnt(2)
	v_add_f32_e32 v70, v70, v71
	ds_bpermute_b32 v94, v65, v70
	v_add_f32_e32 v71, v75, v92
	s_waitcnt lgkmcnt(2)
	v_add_f32_e32 v69, v69, v72
	ds_bpermute_b32 v93, v64, v69
	ds_bpermute_b32 v72, v65, v71
	s_waitcnt lgkmcnt(2)
	v_add_f32_e32 v70, v70, v94
	v_fmamk_f32 v70, v70, 0x3a800000, v67
	v_mul_f32_e32 v75, 0x4b800000, v70
	v_cmp_gt_f32_e64 s[8:9], s18, v70
	s_waitcnt lgkmcnt(1)
	v_add_f32_e32 v69, v69, v93
	v_cndmask_b32_e64 v70, v70, v75, s[8:9]
	v_rsq_f32_e32 v75, v70
	ds_bpermute_b32 v70, v65, v69
	v_mul_f32_e32 v92, 0x45800000, v75
	v_cndmask_b32_e64 v92, v75, v92, s[8:9]
	v_pk_mul_f32 v[76:77], v[76:77], v[92:93] op_sel_hi:[1,0]
	v_pk_mul_f32 v[78:79], v[78:79], v[92:93] op_sel_hi:[1,0]
	v_cvt_pk_bf16_f32 v76, v76, v77
	v_cvt_pk_bf16_f32 v77, v78, v79
	global_store_dwordx2 v[58:59], v[76:77], off sc1
	v_pk_mul_f32 v[76:77], v[80:81], v[92:93] op_sel_hi:[1,0]
	v_pk_mul_f32 v[78:79], v[82:83], v[92:93] op_sel_hi:[1,0]
	v_cvt_pk_bf16_f32 v76, v76, v77
	v_cvt_pk_bf16_f32 v77, v78, v79
	global_store_dwordx2 v[58:59], v[76:77], off offset:512 sc1
	v_pk_mul_f32 v[76:77], v[84:85], v[92:93] op_sel_hi:[1,0]
	v_pk_mul_f32 v[78:79], v[86:87], v[92:93] op_sel_hi:[1,0]
	v_cvt_pk_bf16_f32 v76, v76, v77
	v_cvt_pk_bf16_f32 v77, v78, v79
	global_store_dwordx2 v[58:59], v[76:77], off offset:1024 sc1
	v_pk_mul_f32 v[76:77], v[88:89], v[92:93] op_sel_hi:[1,0]
	v_pk_mul_f32 v[78:79], v[90:91], v[92:93] op_sel_hi:[1,0]
	v_cvt_pk_bf16_f32 v76, v76, v77
	v_cvt_pk_bf16_f32 v77, v78, v79
	global_store_dwordx2 v[58:59], v[76:77], off offset:1536 sc1
	s_and_saveexec_b64 s[8:9], s[6:7]
	s_cbranch_execnz .Lrnp2_a871
	s_or_b64 exec, exec, s[8:9]
	s_and_saveexec_b64 s[6:7], s[0:1]
	s_cbranch_execnz .Lrnp2_a872

.Lrnp2_bt:
	s_or_b64 exec, exec, s[6:7]
	v_cmp_gt_i32_e64 s[4:5], s3, v182
	v_subrev_u32_e32 v113, s16, v182
	v_cmp_gt_i32_e64 s[0:1], s3, v113
	v_subrev_u32_e32 v113, s16, v113
	v_cmp_gt_i32_e64 s[6:7], s3, v113
	s_nop 1
	s_waitcnt vmcnt(15)
	v_pk_mul_f32 v[70:71], v[158:159], v[158:159]
	s_waitcnt vmcnt(14)
	v_pk_mul_f32 v[74:75], v[154:155], v[154:155]
	v_pk_mul_f32 v[72:73], v[160:161], v[160:161]
	v_pk_mul_f32 v[92:93], v[156:157], v[156:157]
	s_waitcnt vmcnt(13)
	v_pk_mul_f32 v[94:95], v[150:151], v[150:151]
	v_add_f32_e32 v69, v74, v75
	v_add_f32_e32 v110, v70, v71
	v_pk_mul_f32 v[96:97], v[152:153], v[152:153]
	s_waitcnt vmcnt(12)
	v_pk_mul_f32 v[98:99], v[146:147], v[146:147]
	v_add_f32_e32 v111, v94, v95
	v_add_f32_e32 v69, v69, v92
	v_add_f32_e32 v72, v110, v72
	v_pk_mul_f32 v[100:101], v[148:149], v[148:149]
	v_add_f32_e32 v112, v98, v99
	v_add_f32_e32 v92, v111, v96
	v_add_f32_e32 v69, v69, v93
	v_add_f32_e32 v72, v72, v73
	v_add_f32_e32 v96, v112, v100
	v_add_f32_e32 v73, v92, v97
	v_add_f32_e32 v69, v72, v69
	v_add_f32_e32 v92, v96, v101
	v_add_f32_e32 v69, v69, v73
	s_waitcnt vmcnt(11)
	v_pk_mul_f32 v[70:71], v[142:143], v[142:143]
	s_waitcnt vmcnt(9)
	v_pk_mul_f32 v[102:103], v[134:135], v[134:135]
	v_add_f32_e32 v69, v69, v92
	v_add_f32_e32 v70, v70, v71
	v_add_f32_e32 v71, v102, v103
	ds_bpermute_b32 v103, v60, v69
	v_pk_mul_f32 v[74:75], v[144:145], v[144:145]
	v_pk_mul_f32 v[94:95], v[138:139], v[138:139]
	v_pk_mul_f32 v[98:99], v[140:141], v[140:141]
	v_add_f32_e32 v94, v94, v95
	v_add_f32_e32 v70, v70, v74
	v_pk_mul_f32 v[104:105], v[136:137], v[136:137]
	v_add_f32_e32 v72, v94, v98
	v_add_f32_e32 v70, v70, v75
	s_waitcnt vmcnt(6)
	v_pk_mul_f32 v[74:75], v[122:123], v[122:123]
	s_waitcnt lgkmcnt(0)
	v_add_f32_e32 v69, v69, v103
	v_add_f32_e32 v72, v72, v99
	v_add_f32_e32 v71, v71, v104
	v_add_f32_e32 v74, v74, v75
	ds_bpermute_b32 v75, v61, v69
	v_pk_mul_f32 v[106:107], v[130:131], v[130:131]
	v_add_f32_e32 v70, v70, v72
	v_add_f32_e32 v71, v71, v105
	v_pk_mul_f32 v[108:109], v[132:133], v[132:133]
	v_add_f32_e32 v70, v70, v71
	v_add_f32_e32 v71, v106, v107
	v_add_f32_e32 v71, v71, v108
	v_add_f32_e32 v71, v71, v109
	v_add_f32_e32 v102, v70, v71
	v_pk_mul_f32 v[70:71], v[126:127], v[126:127]
	s_waitcnt lgkmcnt(0)
	v_add_f32_e32 v69, v69, v75
	v_add_f32_e32 v70, v70, v71
	ds_bpermute_b32 v71, v62, v69
	v_pk_mul_f32 v[72:73], v[128:129], v[128:129]
	v_pk_mul_f32 v[92:93], v[124:125], v[124:125]
	s_waitcnt vmcnt(5)
	v_pk_mul_f32 v[94:95], v[118:119], v[118:119]
	v_pk_mul_f32 v[96:97], v[120:121], v[120:121]
	s_waitcnt lgkmcnt(0)
	v_add_f32_e32 v69, v69, v71
	v_add_f32_e32 v74, v74, v92
	v_add_f32_e32 v70, v70, v72
	v_add_f32_e32 v72, v94, v95
	ds_bpermute_b32 v71, v63, v69
	v_add_f32_e32 v74, v74, v93
	v_add_f32_e32 v70, v70, v73
	v_add_f32_e32 v72, v72, v96
	s_waitcnt vmcnt(4)
	v_pk_mul_f32 v[98:99], v[114:115], v[114:115]
	v_add_f32_e32 v70, v70, v74
	v_add_f32_e32 v72, v72, v97
	v_pk_mul_f32 v[100:101], v[116:117], v[116:117]
	v_add_f32_e32 v96, v70, v72
	v_add_f32_e32 v70, v98, v99
	s_waitcnt vmcnt(3)
	v_mov_b32_e32 v92, v191
	s_waitcnt vmcnt(2)
	v_mov_b32_e32 v93, v195
	v_add_f32_e32 v70, v70, v100
	v_mov_b32_e32 v74, v190
	v_mov_b32_e32 v75, v194
	v_pk_mul_f32 v[92:93], v[92:93], v[92:93]
	v_add_f32_e32 v97, v70, v101
	s_waitcnt lgkmcnt(0)
	v_add_f32_e32 v69, v69, v71
	v_mov_b32_e32 v70, v192
	v_mov_b32_e32 v71, v196
	v_pk_fma_f32 v[74:75], v[74:75], v[74:75], v[92:93]
	s_waitcnt vmcnt(1)
	v_mov_b32_e32 v94, v199
	s_waitcnt vmcnt(0)
	v_mov_b32_e32 v95, v203
	v_mov_b32_e32 v72, v193
	v_mov_b32_e32 v73, v197
	v_pk_fma_f32 v[70:71], v[70:71], v[70:71], v[74:75]
	v_mov_b32_e32 v92, v198
	v_mov_b32_e32 v93, v202
	v_pk_mul_f32 v[94:95], v[94:95], v[94:95]
	v_pk_fma_f32 v[70:71], v[72:73], v[72:73], v[70:71]
	v_mov_b32_e32 v72, v200
	v_mov_b32_e32 v73, v204
	v_pk_fma_f32 v[92:93], v[92:93], v[92:93], v[94:95]
	v_mov_b32_e32 v74, v201
	v_mov_b32_e32 v75, v205
	v_pk_fma_f32 v[72:73], v[72:73], v[72:73], v[92:93]
	v_add_f32_e32 v70, v70, v71
	v_pk_fma_f32 v[72:73], v[74:75], v[74:75], v[72:73]
	ds_bpermute_b32 v74, v60, v102
	v_add_f32_e32 v70, v70, v72
	v_add_f32_e32 v70, v70, v73
	ds_bpermute_b32 v71, v60, v70
	ds_bpermute_b32 v98, v64, v69
	s_waitcnt lgkmcnt(2)
	v_add_f32_e32 v74, v102, v74
	ds_bpermute_b32 v75, v61, v74
	v_add_f32_e32 v72, v96, v97
	s_waitcnt lgkmcnt(2)
	v_add_f32_e32 v70, v70, v71
	ds_bpermute_b32 v71, v61, v70
	s_waitcnt lgkmcnt(2)
	v_add_f32_e32 v73, v69, v98
	ds_bpermute_b32 v69, v60, v72
	s_waitcnt lgkmcnt(2)
	v_add_f32_e32 v74, v74, v75
	ds_bpermute_b32 v75, v62, v74
	s_waitcnt lgkmcnt(2)
	v_add_f32_e32 v70, v70, v71
	ds_bpermute_b32 v71, v62, v70
	s_waitcnt lgkmcnt(2)
	v_add_f32_e32 v69, v72, v69
	ds_bpermute_b32 v72, v61, v69
	s_waitcnt lgkmcnt(2)
	v_add_f32_e32 v74, v74, v75
	ds_bpermute_b32 v75, v63, v74
	s_waitcnt lgkmcnt(2)
	v_add_f32_e32 v70, v70, v71
	ds_bpermute_b32 v71, v63, v70
	s_waitcnt lgkmcnt(2)
	v_add_f32_e32 v69, v69, v72
	ds_bpermute_b32 v72, v62, v69
	s_waitcnt lgkmcnt(2)
	v_add_f32_e32 v75, v74, v75
	ds_bpermute_b32 v92, v64, v75
	s_waitcnt lgkmcnt(2)
	v_add_f32_e32 v70, v70, v71
	ds_bpermute_b32 v71, v64, v70
	s_waitcnt lgkmcnt(2)
	v_add_f32_e32 v69, v69, v72
	ds_bpermute_b32 v72, v63, v69
	ds_bpermute_b32 v74, v65, v73
	s_waitcnt lgkmcnt(2)
	v_add_f32_e32 v70, v70, v71
	ds_bpermute_b32 v94, v65, v70
	v_add_f32_e32 v71, v75, v92
	s_waitcnt lgkmcnt(2)
	v_add_f32_e32 v69, v69, v72
	ds_bpermute_b32 v93, v64, v69
	ds_bpermute_b32 v72, v65, v71
	s_waitcnt lgkmcnt(2)
	v_add_f32_e32 v70, v70, v94
	v_fmamk_f32 v70, v70, 0x3a800000, v67
	v_mul_f32_e32 v75, 0x4b800000, v70
	v_cmp_gt_f32_e64 s[8:9], s18, v70
	s_waitcnt lgkmcnt(1)
	v_add_f32_e32 v69, v69, v93
	v_cndmask_b32_e64 v70, v70, v75, s[8:9]
	v_rsq_f32_e32 v75, v70
	ds_bpermute_b32 v70, v65, v69
	v_mul_f32_e32 v92, 0x45800000, v75
	v_cndmask_b32_e64 v92, v75, v92, s[8:9]
	v_pk_mul_f32 v[190:191], v[190:191], v[92:93] op_sel_hi:[1,0]
	v_pk_mul_f32 v[192:193], v[192:193], v[92:93] op_sel_hi:[1,0]
	v_cvt_pk_bf16_f32 v190, v190, v191
	v_cvt_pk_bf16_f32 v191, v192, v193
	global_store_dwordx2 v[172:173], v[190:191], off sc1
	v_pk_mul_f32 v[190:191], v[194:195], v[92:93] op_sel_hi:[1,0]
	v_pk_mul_f32 v[192:193], v[196:197], v[92:93] op_sel_hi:[1,0]
	v_cvt_pk_bf16_f32 v190, v190, v191
	v_cvt_pk_bf16_f32 v191, v192, v193
	global_store_dwordx2 v[172:173], v[190:191], off offset:512 sc1
	v_pk_mul_f32 v[190:191], v[198:199], v[92:93] op_sel_hi:[1,0]
	v_pk_mul_f32 v[192:193], v[200:201], v[92:93] op_sel_hi:[1,0]
	v_cvt_pk_bf16_f32 v190, v190, v191
	v_cvt_pk_bf16_f32 v191, v192, v193
	global_store_dwordx2 v[172:173], v[190:191], off offset:1024 sc1
	v_pk_mul_f32 v[190:191], v[202:203], v[92:93] op_sel_hi:[1,0]
	v_pk_mul_f32 v[192:193], v[204:205], v[92:93] op_sel_hi:[1,0]
	v_cvt_pk_bf16_f32 v190, v190, v191
	v_cvt_pk_bf16_f32 v191, v192, v193
	global_store_dwordx2 v[172:173], v[190:191], off offset:1536 sc1
	s_and_saveexec_b64 s[8:9], s[6:7]
	s_cbranch_execnz .Lrnp2_b871
	s_or_b64 exec, exec, s[8:9]
	s_and_saveexec_b64 s[6:7], s[0:1]
	s_cbranch_execnz .Lrnp2_b872

.Lrnp2_b871:
	v_add_f32_e32 v172, v73, v74
	v_fmamk_f32 v172, v172, 0x3a800000, v67
	v_mul_f32_e32 v173, 0x4b800000, v172
	v_cmp_gt_f32_e64 s[6:7], s18, v172
	v_lshlrev_b64 v[170:171], 11, v[170:171]
	s_nop 0
	v_cndmask_b32_e64 v172, v172, v173, s[6:7]
	v_rsq_f32_e32 v172, v172
	s_nop 0
	v_mul_f32_e32 v173, 0x45800000, v172
	v_cndmask_b32_e64 v172, v172, v173, s[6:7]
	v_pk_mul_f32 v[158:159], v[158:159], v[172:173] op_sel_hi:[1,0]
	v_pk_mul_f32 v[160:161], v[160:161], v[172:173] op_sel_hi:[1,0]
	v_pk_mul_f32 v[154:155], v[154:155], v[172:173] op_sel_hi:[1,0]
	v_pk_mul_f32 v[156:157], v[156:157], v[172:173] op_sel_hi:[1,0]
	v_pk_mul_f32 v[150:151], v[150:151], v[172:173] op_sel_hi:[1,0]
	v_pk_mul_f32 v[152:153], v[152:153], v[172:173] op_sel_hi:[1,0]
	v_pk_mul_f32 v[146:147], v[146:147], v[172:173] op_sel_hi:[1,0]
	v_pk_mul_f32 v[148:149], v[148:149], v[172:173] op_sel_hi:[1,0]
	v_cvt_pk_bf16_f32 v158, v158, v159
	v_cvt_pk_bf16_f32 v159, v160, v161
	v_lshl_add_u64 v[160:161], v[48:49], 0, v[170:171]
	v_cvt_pk_bf16_f32 v154, v154, v155
	v_cvt_pk_bf16_f32 v155, v156, v157
	v_cvt_pk_bf16_f32 v150, v150, v151
	v_cvt_pk_bf16_f32 v151, v152, v153
	v_cvt_pk_bf16_f32 v146, v146, v147
	v_cvt_pk_bf16_f32 v147, v148, v149
	global_store_dwordx2 v[160:161], v[158:159], off sc1
	global_store_dwordx2 v[160:161], v[154:155], off offset:512 sc1
	global_store_dwordx2 v[160:161], v[150:151], off offset:1024 sc1
	global_store_dwordx2 v[160:161], v[146:147], off offset:1536 sc1
	s_or_b64 exec, exec, s[8:9]
	s_and_saveexec_b64 s[6:7], s[0:1]
	s_cbranch_execz .Lrnp2_b870
.Lrnp2_b872:
	s_waitcnt lgkmcnt(1)
	v_add_f32_e32 v146, v71, v72
	v_fmamk_f32 v146, v146, 0x3a800000, v67
	v_mul_f32_e32 v147, 0x4b800000, v146
	v_cmp_gt_f32_e64 s[0:1], s18, v146
	s_nop 1
	v_cndmask_b32_e64 v146, v146, v147, s[0:1]
	v_rsq_f32_e32 v148, v146
	v_lshlrev_b64 v[146:147], 11, v[168:169]
	v_mul_f32_e32 v149, 0x45800000, v148
	v_cndmask_b32_e64 v148, v148, v149, s[0:1]
	v_pk_mul_f32 v[142:143], v[142:143], v[148:149] op_sel_hi:[1,0]
	v_pk_mul_f32 v[144:145], v[144:145], v[148:149] op_sel_hi:[1,0]
	v_pk_mul_f32 v[138:139], v[138:139], v[148:149] op_sel_hi:[1,0]
	v_pk_mul_f32 v[140:141], v[140:141], v[148:149] op_sel_hi:[1,0]
	v_pk_mul_f32 v[134:135], v[134:135], v[148:149] op_sel_hi:[1,0]
	v_pk_mul_f32 v[136:137], v[136:137], v[148:149] op_sel_hi:[1,0]
	v_pk_mul_f32 v[130:131], v[130:131], v[148:149] op_sel_hi:[1,0]
	v_pk_mul_f32 v[132:133], v[132:133], v[148:149] op_sel_hi:[1,0]
	v_cvt_pk_bf16_f32 v142, v142, v143
	v_cvt_pk_bf16_f32 v143, v144, v145
	v_lshl_add_u64 v[144:145], v[48:49], 0, v[146:147]
	v_cvt_pk_bf16_f32 v138, v138, v139
	v_cvt_pk_bf16_f32 v139, v140, v141
	v_cvt_pk_bf16_f32 v134, v134, v135
	v_cvt_pk_bf16_f32 v135, v136, v137
	v_cvt_pk_bf16_f32 v130, v130, v131
	v_cvt_pk_bf16_f32 v131, v132, v133
	global_store_dwordx2 v[144:145], v[142:143], off sc1
	global_store_dwordx2 v[144:145], v[138:139], off offset:512 sc1
	global_store_dwordx2 v[144:145], v[134:135], off offset:1024 sc1
	global_store_dwordx2 v[144:145], v[130:131], off offset:1536 sc1
	s_or_b64 exec, exec, s[6:7]
	s_and_saveexec_b64 s[6:7], s[4:5]
	s_cbranch_execz .Lrnp2_bc
.Lrnp2_b873:
	s_waitcnt lgkmcnt(0)
	v_add_f32_e32 v130, v69, v70
	v_fmamk_f32 v130, v130, 0x3a800000, v67
	v_mul_f32_e32 v131, 0x4b800000, v130
	v_cmp_gt_f32_e64 s[0:1], s18, v130
	s_nop 1
	v_cndmask_b32_e64 v130, v130, v131, s[0:1]
	v_rsq_f32_e32 v132, v130
	v_lshlrev_b64 v[130:131], 11, v[166:167]
	v_mul_f32_e32 v133, 0x45800000, v132
	v_cndmask_b32_e64 v132, v132, v133, s[0:1]
	v_pk_mul_f32 v[126:127], v[126:127], v[132:133] op_sel_hi:[1,0]
	v_pk_mul_f32 v[128:129], v[128:129], v[132:133] op_sel_hi:[1,0]
	v_pk_mul_f32 v[122:123], v[122:123], v[132:133] op_sel_hi:[1,0]
	v_pk_mul_f32 v[124:125], v[124:125], v[132:133] op_sel_hi:[1,0]
	v_pk_mul_f32 v[118:119], v[118:119], v[132:133] op_sel_hi:[1,0]
	v_pk_mul_f32 v[120:121], v[120:121], v[132:133] op_sel_hi:[1,0]
	v_pk_mul_f32 v[114:115], v[114:115], v[132:133] op_sel_hi:[1,0]
	v_pk_mul_f32 v[116:117], v[116:117], v[132:133] op_sel_hi:[1,0]
	v_cvt_pk_bf16_f32 v126, v126, v127
	v_cvt_pk_bf16_f32 v127, v128, v129
	v_lshl_add_u64 v[128:129], v[48:49], 0, v[130:131]
	v_cvt_pk_bf16_f32 v122, v122, v123
	v_cvt_pk_bf16_f32 v123, v124, v125
	v_cvt_pk_bf16_f32 v118, v118, v119
	v_cvt_pk_bf16_f32 v119, v120, v121
	v_cvt_pk_bf16_f32 v114, v114, v115
	v_cvt_pk_bf16_f32 v115, v116, v117
	global_store_dwordx2 v[128:129], v[126:127], off sc1
	global_store_dwordx2 v[128:129], v[122:123], off offset:512 sc1
	global_store_dwordx2 v[128:129], v[118:119], off offset:1024 sc1
	global_store_dwordx2 v[128:129], v[114:115], off offset:1536 sc1
	s_branch .Lrnp2_bc
.Lrnp2_bc:
	s_or_b64 exec, exec, s[6:7]
	v_add_u32_e32 v58, s16, v182
	v_cmp_lt_i32_e64 s[0:1], s19, v58
	s_or_b64 s[14:15], s[0:1], s[14:15]
	v_add_u32_e32 v66, s17, v180
	s_andn2_b64 exec, exec, s[14:15]
	s_cbranch_execz .LBB0_874
	s_branch .LBB0_868
.Lrnp2_orig:
	s_waitcnt vmcnt(15)
	v_pk_mul_f32 v[70:71], v[44:45], v[44:45]
	s_waitcnt vmcnt(14)
	v_pk_mul_f32 v[74:75], v[40:41], v[40:41]
	v_pk_mul_f32 v[72:73], v[46:47], v[46:47]
	v_pk_mul_f32 v[92:93], v[42:43], v[42:43]
	s_waitcnt vmcnt(13)
	v_pk_mul_f32 v[94:95], v[36:37], v[36:37]
	v_add_f32_e32 v69, v74, v75
	v_add_f32_e32 v110, v70, v71
	v_pk_mul_f32 v[96:97], v[38:39], v[38:39]
	s_waitcnt vmcnt(12)
	v_pk_mul_f32 v[98:99], v[32:33], v[32:33]
	v_add_f32_e32 v111, v94, v95
	v_add_f32_e32 v69, v69, v92
	v_add_f32_e32 v72, v110, v72
	v_pk_mul_f32 v[100:101], v[34:35], v[34:35]
	v_add_f32_e32 v112, v98, v99
	v_add_f32_e32 v92, v111, v96
	v_add_f32_e32 v69, v69, v93
	v_add_f32_e32 v72, v72, v73
	v_add_f32_e32 v96, v112, v100
	v_add_f32_e32 v73, v92, v97
	v_add_f32_e32 v69, v72, v69
	v_add_f32_e32 v92, v96, v101
	v_add_f32_e32 v69, v69, v73
	s_waitcnt vmcnt(11)
	v_pk_mul_f32 v[70:71], v[28:29], v[28:29]
	s_waitcnt vmcnt(9)
	v_pk_mul_f32 v[102:103], v[20:21], v[20:21]
	v_add_f32_e32 v69, v69, v92
	v_add_f32_e32 v70, v70, v71
	v_add_f32_e32 v71, v102, v103
	ds_bpermute_b32 v103, v60, v69
	v_pk_mul_f32 v[74:75], v[30:31], v[30:31]
	v_pk_mul_f32 v[94:95], v[24:25], v[24:25]
	v_pk_mul_f32 v[98:99], v[26:27], v[26:27]
	v_add_f32_e32 v94, v94, v95
	v_add_f32_e32 v70, v70, v74
	v_pk_mul_f32 v[104:105], v[22:23], v[22:23]
	v_add_f32_e32 v72, v94, v98
	v_add_f32_e32 v70, v70, v75
	s_waitcnt vmcnt(6)
	v_pk_mul_f32 v[74:75], v[8:9], v[8:9]
	s_waitcnt lgkmcnt(0)
	v_add_f32_e32 v69, v69, v103
	v_add_f32_e32 v72, v72, v99
	v_add_f32_e32 v71, v71, v104
	v_add_f32_e32 v74, v74, v75
	ds_bpermute_b32 v75, v61, v69
	v_pk_mul_f32 v[106:107], v[16:17], v[16:17]
	v_add_f32_e32 v70, v70, v72
	v_add_f32_e32 v71, v71, v105
	v_pk_mul_f32 v[108:109], v[18:19], v[18:19]
	v_add_f32_e32 v70, v70, v71
	v_add_f32_e32 v71, v106, v107
	v_add_f32_e32 v71, v71, v108
	v_add_f32_e32 v71, v71, v109
	v_add_f32_e32 v102, v70, v71
	v_pk_mul_f32 v[70:71], v[12:13], v[12:13]
	s_waitcnt lgkmcnt(0)
	v_add_f32_e32 v69, v69, v75
	v_add_f32_e32 v70, v70, v71
	ds_bpermute_b32 v71, v62, v69
	v_pk_mul_f32 v[72:73], v[14:15], v[14:15]
	v_pk_mul_f32 v[92:93], v[10:11], v[10:11]
	s_waitcnt vmcnt(5)
	v_pk_mul_f32 v[94:95], v[4:5], v[4:5]
	v_pk_mul_f32 v[96:97], v[6:7], v[6:7]
	s_waitcnt lgkmcnt(0)
	v_add_f32_e32 v69, v69, v71
	v_add_f32_e32 v74, v74, v92
	v_add_f32_e32 v70, v70, v72
	v_add_f32_e32 v72, v94, v95
	ds_bpermute_b32 v71, v63, v69
	v_add_f32_e32 v74, v74, v93
	v_add_f32_e32 v70, v70, v73
	v_add_f32_e32 v72, v72, v96
	s_waitcnt vmcnt(4)
	v_pk_mul_f32 v[98:99], v[0:1], v[0:1]
	v_add_f32_e32 v70, v70, v74
	v_add_f32_e32 v72, v72, v97
	v_pk_mul_f32 v[100:101], v[2:3], v[2:3]
	v_add_f32_e32 v96, v70, v72
	v_add_f32_e32 v70, v98, v99
	s_waitcnt vmcnt(3)
	v_mov_b32_e32 v92, v77
	s_waitcnt vmcnt(2)
	v_mov_b32_e32 v93, v81
	v_add_f32_e32 v70, v70, v100
	v_mov_b32_e32 v74, v76
	v_mov_b32_e32 v75, v80
	v_pk_mul_f32 v[92:93], v[92:93], v[92:93]
	v_add_f32_e32 v97, v70, v101
	s_waitcnt lgkmcnt(0)
	v_add_f32_e32 v69, v69, v71
	v_mov_b32_e32 v70, v78
	v_mov_b32_e32 v71, v82
	v_pk_fma_f32 v[74:75], v[74:75], v[74:75], v[92:93]
	s_waitcnt vmcnt(1)
	v_mov_b32_e32 v94, v85
	s_waitcnt vmcnt(0)
	v_mov_b32_e32 v95, v89
	v_mov_b32_e32 v72, v79
	v_mov_b32_e32 v73, v83
	v_pk_fma_f32 v[70:71], v[70:71], v[70:71], v[74:75]
	v_mov_b32_e32 v92, v84
	v_mov_b32_e32 v93, v88
	v_pk_mul_f32 v[94:95], v[94:95], v[94:95]
	v_pk_fma_f32 v[70:71], v[72:73], v[72:73], v[70:71]
	v_mov_b32_e32 v72, v86
	v_mov_b32_e32 v73, v90
	v_pk_fma_f32 v[92:93], v[92:93], v[92:93], v[94:95]
	v_mov_b32_e32 v74, v87
	v_mov_b32_e32 v75, v91
	v_pk_fma_f32 v[72:73], v[72:73], v[72:73], v[92:93]
	v_add_f32_e32 v70, v70, v71
	v_pk_fma_f32 v[72:73], v[74:75], v[74:75], v[72:73]
	ds_bpermute_b32 v74, v60, v102
	v_add_f32_e32 v70, v70, v72
	v_add_f32_e32 v70, v70, v73
	ds_bpermute_b32 v71, v60, v70
	ds_bpermute_b32 v98, v64, v69
	s_waitcnt lgkmcnt(2)
	v_add_f32_e32 v74, v102, v74
	ds_bpermute_b32 v75, v61, v74
	v_add_f32_e32 v72, v96, v97
	s_waitcnt lgkmcnt(2)
	v_add_f32_e32 v70, v70, v71
	ds_bpermute_b32 v71, v61, v70
	s_waitcnt lgkmcnt(2)
	v_add_f32_e32 v73, v69, v98
	ds_bpermute_b32 v69, v60, v72
	s_waitcnt lgkmcnt(2)
	v_add_f32_e32 v74, v74, v75
	ds_bpermute_b32 v75, v62, v74
	s_waitcnt lgkmcnt(2)
	v_add_f32_e32 v70, v70, v71
	ds_bpermute_b32 v71, v62, v70
	s_waitcnt lgkmcnt(2)
	v_add_f32_e32 v69, v72, v69
	ds_bpermute_b32 v72, v61, v69
	s_waitcnt lgkmcnt(2)
	v_add_f32_e32 v74, v74, v75
	ds_bpermute_b32 v75, v63, v74
	s_waitcnt lgkmcnt(2)
	v_add_f32_e32 v70, v70, v71
	ds_bpermute_b32 v71, v63, v70
	s_waitcnt lgkmcnt(2)
	v_add_f32_e32 v69, v69, v72
	ds_bpermute_b32 v72, v62, v69
	s_waitcnt lgkmcnt(2)
	v_add_f32_e32 v75, v74, v75
	ds_bpermute_b32 v92, v64, v75
	s_waitcnt lgkmcnt(2)
	v_add_f32_e32 v70, v70, v71
	ds_bpermute_b32 v71, v64, v70
	s_waitcnt lgkmcnt(2)
	v_add_f32_e32 v69, v69, v72
	ds_bpermute_b32 v72, v63, v69
	ds_bpermute_b32 v74, v65, v73
	s_waitcnt lgkmcnt(2)
	v_add_f32_e32 v70, v70, v71
	ds_bpermute_b32 v94, v65, v70
	v_add_f32_e32 v71, v75, v92
	s_waitcnt lgkmcnt(2)
	v_add_f32_e32 v69, v69, v72
	ds_bpermute_b32 v93, v64, v69
	ds_bpermute_b32 v72, v65, v71
	s_waitcnt lgkmcnt(2)
	v_add_f32_e32 v70, v70, v94
	v_fmamk_f32 v70, v70, 0x3a800000, v67
	v_mul_f32_e32 v75, 0x4b800000, v70
	v_cmp_gt_f32_e64 s[8:9], s18, v70
	s_waitcnt lgkmcnt(1)
	v_add_f32_e32 v69, v69, v93
	v_cndmask_b32_e64 v70, v70, v75, s[8:9]
	v_rsq_f32_e32 v75, v70
	ds_bpermute_b32 v70, v65, v69
	v_mul_f32_e32 v92, 0x45800000, v75
	v_cndmask_b32_e64 v92, v75, v92, s[8:9]
	v_pk_mul_f32 v[76:77], v[76:77], v[92:93] op_sel_hi:[1,0]
	v_pk_mul_f32 v[78:79], v[78:79], v[92:93] op_sel_hi:[1,0]
	v_cvt_pk_bf16_f32 v76, v76, v77
	v_cvt_pk_bf16_f32 v77, v78, v79
	global_store_dwordx2 v[58:59], v[76:77], off sc1
	v_pk_mul_f32 v[76:77], v[80:81], v[92:93] op_sel_hi:[1,0]
	v_pk_mul_f32 v[78:79], v[82:83], v[92:93] op_sel_hi:[1,0]
	v_cvt_pk_bf16_f32 v76, v76, v77
	v_cvt_pk_bf16_f32 v77, v78, v79
	global_store_dwordx2 v[58:59], v[76:77], off offset:512 sc1
	v_pk_mul_f32 v[76:77], v[84:85], v[92:93] op_sel_hi:[1,0]
	v_pk_mul_f32 v[78:79], v[86:87], v[92:93] op_sel_hi:[1,0]
	v_cvt_pk_bf16_f32 v76, v76, v77
	v_cvt_pk_bf16_f32 v77, v78, v79
	global_store_dwordx2 v[58:59], v[76:77], off offset:1024 sc1
	v_pk_mul_f32 v[76:77], v[88:89], v[92:93] op_sel_hi:[1,0]
	v_pk_mul_f32 v[78:79], v[90:91], v[92:93] op_sel_hi:[1,0]
	v_cvt_pk_bf16_f32 v76, v76, v77
	v_cvt_pk_bf16_f32 v77, v78, v79
	global_store_dwordx2 v[58:59], v[76:77], off offset:1536 sc1
	s_and_saveexec_b64 s[8:9], s[6:7]
	s_cbranch_execnz .LBB0_871
	s_or_b64 exec, exec, s[8:9]
	s_and_saveexec_b64 s[6:7], s[0:1]
	s_cbranch_execnz .LBB0_872

.LBB0_1423:
	v_add_u32_e32 v0, s16, v58
	v_cmp_gt_i32_e64 s[6:7], s3, v0
	v_lshrrev_b32_e32 v69, 3, v58
	v_and_b32_e32 v59, 0x700, v66
	v_cndmask_b32_e64 v1, v58, v0, s[6:7]
	v_lshlrev_b32_e32 v2, 5, v1
	v_lshrrev_b32_e32 v3, 3, v1
	v_and_b32_e32 v2, 0x700, v2
	v_and_b32_e32 v3, 0xf8, v3
	v_and_b32_e32 v4, 0xfffff807, v1
	v_or3_b32 v2, v2, v4, v3
	v_cndmask_b32_e32 v56, v1, v2, vcc
	v_add_u32_e32 v2, s16, v0
	v_cmp_gt_i32_e64 s[0:1], s3, v2
	v_ashrrev_i32_e32 v57, 31, v56
	v_add_u32_e32 v68, s16, v2
	v_cndmask_b32_e64 v3, v58, v2, s[0:1]
	v_lshlrev_b32_e32 v0, 5, v3
	v_and_b32_e32 v4, 0x700, v0
	v_lshlrev_b64 v[0:1], 12, v[56:57]
	v_lshl_add_u64 v[0:1], v[50:51], 0, v[0:1]
	v_lshrrev_b32_e32 v5, 3, v3
	global_load_dwordx4 v[44:47], v[0:1], off
	global_load_dwordx4 v[40:43], v[0:1], off offset:1024
	v_and_b32_e32 v5, 0xf8, v5
	v_and_b32_e32 v6, 0xfffff807, v3
	global_load_dwordx4 v[36:39], v[0:1], off offset:2048
	global_load_dwordx4 v[32:35], v[0:1], off offset:3072
	v_or3_b32 v0, v4, v6, v5
	v_cndmask_b32_e32 v54, v3, v0, vcc
	v_ashrrev_i32_e32 v55, 31, v54
	v_lshlrev_b64 v[0:1], 12, v[54:55]
	v_lshl_add_u64 v[0:1], v[50:51], 0, v[0:1]
	v_cmp_gt_i32_e64 s[4:5], s3, v68
	global_load_dwordx4 v[28:31], v[0:1], off
	global_load_dwordx4 v[24:27], v[0:1], off offset:1024
	global_load_dwordx4 v[20:23], v[0:1], off offset:2048
	global_load_dwordx4 v[16:19], v[0:1], off offset:3072
	v_cndmask_b32_e64 v0, v58, v68, s[4:5]
	v_lshlrev_b32_e32 v1, 5, v0
	v_lshrrev_b32_e32 v2, 3, v0
	v_and_b32_e32 v3, 0xfffff807, v0
	v_and_b32_e32 v1, 0x700, v1
	v_and_b32_e32 v2, 0xf8, v2
	v_or3_b32 v1, v1, v3, v2
	v_cndmask_b32_e32 v52, v0, v1, vcc
	v_ashrrev_i32_e32 v53, 31, v52
	v_lshlrev_b64 v[0:1], 12, v[52:53]
	s_waitcnt lgkmcnt(0)
	v_lshl_add_u64 v[70:71], v[50:51], 0, v[0:1]
	global_load_dwordx4 v[12:15], v[70:71], off
	global_load_dwordx4 v[8:11], v[70:71], off offset:1024
	global_load_dwordx4 v[4:7], v[70:71], off offset:2048
	global_load_dwordx4 v[0:3], v[70:71], off offset:3072
	v_and_b32_e32 v70, 0xfffff807, v58
	v_and_b32_e32 v69, 0xf8, v69
	v_or3_b32 v59, v59, v70, v69
	v_cndmask_b32_e32 v58, v58, v59, vcc
	v_ashrrev_i32_e32 v59, 31, v58
	v_lshlrev_b64 v[70:71], 12, v[58:59]
	v_lshl_add_u64 v[70:71], v[50:51], 0, v[70:71]
	global_load_dwordx4 v[76:79], v[70:71], off
	global_load_dwordx4 v[80:83], v[70:71], off offset:1024
	global_load_dwordx4 v[84:87], v[70:71], off offset:2048
	global_load_dwordx4 v[88:91], v[70:71], off offset:3072
	v_lshlrev_b64 v[58:59], 11, v[58:59]
	v_lshl_add_u64 v[58:59], v[48:49], 0, v[58:59]
	v_add_u32_e32 v172, s16, v68
	v_add_u32_e32 v180, s17, v66
	v_cmp_ge_i32_e64 s[8:9], s19, v172
	s_nop 1
	s_and_b64 s[8:9], s[8:9], exec
	s_cbranch_scc0 .Lrnp3_orig
	v_add_u32_e32 v114, s16, v172
	v_cmp_gt_i32_e64 s[8:9], s3, v114
	v_lshrrev_b32_e32 v183, 3, v172
	v_and_b32_e32 v173, 0x700, v180
	v_cndmask_b32_e64 v115, v172, v114, s[8:9]
	v_lshlrev_b32_e32 v116, 5, v115
	v_lshrrev_b32_e32 v117, 3, v115
	v_and_b32_e32 v116, 0x700, v116
	v_and_b32_e32 v117, 0xf8, v117
	v_and_b32_e32 v118, 0xfffff807, v115
	v_or3_b32 v116, v116, v118, v117
	v_cndmask_b32_e32 v170, v115, v116, vcc
	v_add_u32_e32 v116, s16, v114
	v_cmp_gt_i32_e64 s[8:9], s3, v116
	v_ashrrev_i32_e32 v171, 31, v170
	v_add_u32_e32 v182, s16, v116
	v_cndmask_b32_e64 v117, v172, v116, s[8:9]
	v_lshlrev_b32_e32 v114, 5, v117
	v_and_b32_e32 v118, 0x700, v114
	v_lshlrev_b64 v[114:115], 12, v[170:171]
	v_lshl_add_u64 v[114:115], v[50:51], 0, v[114:115]
	v_lshrrev_b32_e32 v119, 3, v117
	global_load_dwordx4 v[158:161], v[114:115], off
	global_load_dwordx4 v[154:157], v[114:115], off offset:1024
	v_and_b32_e32 v119, 0xf8, v119
	v_and_b32_e32 v120, 0xfffff807, v117
	global_load_dwordx4 v[150:153], v[114:115], off offset:2048
	global_load_dwordx4 v[146:149], v[114:115], off offset:3072
	v_or3_b32 v114, v118, v120, v119
	v_cndmask_b32_e32 v168, v117, v114, vcc
	v_ashrrev_i32_e32 v169, 31, v168
	v_lshlrev_b64 v[114:115], 12, v[168:169]
	v_lshl_add_u64 v[114:115], v[50:51], 0, v[114:115]
	v_cmp_gt_i32_e64 s[8:9], s3, v182
	global_load_dwordx4 v[142:145], v[114:115], off
	global_load_dwordx4 v[138:141], v[114:115], off offset:1024
	global_load_dwordx4 v[134:137], v[114:115], off offset:2048
	global_load_dwordx4 v[130:133], v[114:115], off offset:3072
	v_cndmask_b32_e64 v114, v172, v182, s[8:9]
	v_lshlrev_b32_e32 v115, 5, v114
	v_lshrrev_b32_e32 v116, 3, v114
	v_and_b32_e32 v117, 0xfffff807, v114
	v_and_b32_e32 v115, 0x700, v115
	v_and_b32_e32 v116, 0xf8, v116
	v_or3_b32 v115, v115, v117, v116
	v_cndmask_b32_e32 v166, v114, v115, vcc
	v_ashrrev_i32_e32 v167, 31, v166
	v_lshlrev_b64 v[114:115], 12, v[166:167]
	s_waitcnt lgkmcnt(0)
	v_lshl_add_u64 v[184:185], v[50:51], 0, v[114:115]
	global_load_dwordx4 v[126:129], v[184:185], off
	global_load_dwordx4 v[122:125], v[184:185], off offset:1024
	global_load_dwordx4 v[118:121], v[184:185], off offset:2048
	global_load_dwordx4 v[114:117], v[184:185], off offset:3072
	v_and_b32_e32 v184, 0xfffff807, v172
	v_and_b32_e32 v183, 0xf8, v183
	v_or3_b32 v173, v173, v184, v183
	v_cndmask_b32_e32 v172, v172, v173, vcc
	v_ashrrev_i32_e32 v173, 31, v172
	v_lshlrev_b64 v[184:185], 12, v[172:173]
	v_lshl_add_u64 v[184:185], v[50:51], 0, v[184:185]
	global_load_dwordx4 v[190:193], v[184:185], off
	global_load_dwordx4 v[194:197], v[184:185], off offset:1024
	global_load_dwordx4 v[198:201], v[184:185], off offset:2048
	global_load_dwordx4 v[202:205], v[184:185], off offset:3072
	v_lshlrev_b64 v[172:173], 11, v[172:173]
	v_lshl_add_u64 v[172:173], v[48:49], 0, v[172:173]
	s_waitcnt vmcnt(31)
	v_pk_mul_f32 v[70:71], v[44:45], v[44:45]
	s_waitcnt vmcnt(30)
	v_pk_mul_f32 v[74:75], v[40:41], v[40:41]
	v_pk_mul_f32 v[72:73], v[46:47], v[46:47]
	v_pk_mul_f32 v[92:93], v[42:43], v[42:43]
	s_waitcnt vmcnt(29)
	v_pk_mul_f32 v[94:95], v[36:37], v[36:37]
	v_add_f32_e32 v69, v74, v75
	v_add_f32_e32 v110, v70, v71
	v_pk_mul_f32 v[96:97], v[38:39], v[38:39]
	s_waitcnt vmcnt(28)
	v_pk_mul_f32 v[98:99], v[32:33], v[32:33]
	v_add_f32_e32 v111, v94, v95
	v_add_f32_e32 v69, v69, v92
	v_add_f32_e32 v72, v110, v72
	v_pk_mul_f32 v[100:101], v[34:35], v[34:35]
	v_add_f32_e32 v112, v98, v99
	v_add_f32_e32 v92, v111, v96
	v_add_f32_e32 v69, v69, v93
	v_add_f32_e32 v72, v72, v73
	v_add_f32_e32 v96, v112, v100
	v_add_f32_e32 v73, v92, v97
	v_add_f32_e32 v69, v72, v69
	v_add_f32_e32 v92, v96, v101
	v_add_f32_e32 v69, v69, v73
	s_waitcnt vmcnt(27)
	v_pk_mul_f32 v[70:71], v[28:29], v[28:29]
	s_waitcnt vmcnt(25)
	v_pk_mul_f32 v[102:103], v[20:21], v[20:21]
	v_add_f32_e32 v69, v69, v92
	v_add_f32_e32 v70, v70, v71
	v_add_f32_e32 v71, v102, v103
	ds_bpermute_b32 v103, v60, v69
	v_pk_mul_f32 v[74:75], v[30:31], v[30:31]
	v_pk_mul_f32 v[94:95], v[24:25], v[24:25]
	v_pk_mul_f32 v[98:99], v[26:27], v[26:27]
	v_add_f32_e32 v94, v94, v95
	v_add_f32_e32 v70, v70, v74
	v_pk_mul_f32 v[104:105], v[22:23], v[22:23]
	v_add_f32_e32 v72, v94, v98
	v_add_f32_e32 v70, v70, v75
	s_waitcnt vmcnt(22)
	v_pk_mul_f32 v[74:75], v[8:9], v[8:9]
	s_waitcnt lgkmcnt(0)
	v_add_f32_e32 v69, v69, v103
	v_add_f32_e32 v72, v72, v99
	v_add_f32_e32 v71, v71, v104
	v_add_f32_e32 v74, v74, v75
	ds_bpermute_b32 v75, v61, v69
	v_pk_mul_f32 v[106:107], v[16:17], v[16:17]
	v_add_f32_e32 v70, v70, v72
	v_add_f32_e32 v71, v71, v105
	v_pk_mul_f32 v[108:109], v[18:19], v[18:19]
	v_add_f32_e32 v70, v70, v71
	v_add_f32_e32 v71, v106, v107
	v_add_f32_e32 v71, v71, v108
	v_add_f32_e32 v71, v71, v109
	v_add_f32_e32 v102, v70, v71
	v_pk_mul_f32 v[70:71], v[12:13], v[12:13]
	s_waitcnt lgkmcnt(0)
	v_add_f32_e32 v69, v69, v75
	v_add_f32_e32 v70, v70, v71
	ds_bpermute_b32 v71, v62, v69
	v_pk_mul_f32 v[72:73], v[14:15], v[14:15]
	v_pk_mul_f32 v[92:93], v[10:11], v[10:11]
	s_waitcnt vmcnt(21)
	v_pk_mul_f32 v[94:95], v[4:5], v[4:5]
	v_pk_mul_f32 v[96:97], v[6:7], v[6:7]
	s_waitcnt lgkmcnt(0)
	v_add_f32_e32 v69, v69, v71
	v_add_f32_e32 v74, v74, v92
	v_add_f32_e32 v70, v70, v72
	v_add_f32_e32 v72, v94, v95
	ds_bpermute_b32 v71, v63, v69
	v_add_f32_e32 v74, v74, v93
	v_add_f32_e32 v70, v70, v73
	v_add_f32_e32 v72, v72, v96
	s_waitcnt vmcnt(20)
	v_pk_mul_f32 v[98:99], v[0:1], v[0:1]
	v_add_f32_e32 v70, v70, v74
	v_add_f32_e32 v72, v72, v97
	v_pk_mul_f32 v[100:101], v[2:3], v[2:3]
	v_add_f32_e32 v96, v70, v72
	v_add_f32_e32 v70, v98, v99
	s_waitcnt vmcnt(19)
	v_mov_b32_e32 v92, v77
	s_waitcnt vmcnt(18)
	v_mov_b32_e32 v93, v81
	v_add_f32_e32 v70, v70, v100
	v_mov_b32_e32 v74, v76
	v_mov_b32_e32 v75, v80
	v_pk_mul_f32 v[92:93], v[92:93], v[92:93]
	v_add_f32_e32 v97, v70, v101
	s_waitcnt lgkmcnt(0)
	v_add_f32_e32 v69, v69, v71
	v_mov_b32_e32 v70, v78
	v_mov_b32_e32 v71, v82
	v_pk_fma_f32 v[74:75], v[74:75], v[74:75], v[92:93]
	s_waitcnt vmcnt(17)
	v_mov_b32_e32 v94, v85
	s_waitcnt vmcnt(16)
	v_mov_b32_e32 v95, v89
	v_mov_b32_e32 v72, v79
	v_mov_b32_e32 v73, v83
	v_pk_fma_f32 v[70:71], v[70:71], v[70:71], v[74:75]
	v_mov_b32_e32 v92, v84
	v_mov_b32_e32 v93, v88
	v_pk_mul_f32 v[94:95], v[94:95], v[94:95]
	v_pk_fma_f32 v[70:71], v[72:73], v[72:73], v[70:71]
	v_mov_b32_e32 v72, v86
	v_mov_b32_e32 v73, v90
	v_pk_fma_f32 v[92:93], v[92:93], v[92:93], v[94:95]
	v_mov_b32_e32 v74, v87
	v_mov_b32_e32 v75, v91
	v_pk_fma_f32 v[72:73], v[72:73], v[72:73], v[92:93]
	v_add_f32_e32 v70, v70, v71
	v_pk_fma_f32 v[72:73], v[74:75], v[74:75], v[72:73]
	ds_bpermute_b32 v74, v60, v102
	v_add_f32_e32 v70, v70, v72
	v_add_f32_e32 v70, v70, v73
	ds_bpermute_b32 v71, v60, v70
	ds_bpermute_b32 v98, v64, v69
	s_waitcnt lgkmcnt(2)
	v_add_f32_e32 v74, v102, v74
	ds_bpermute_b32 v75, v61, v74
	v_add_f32_e32 v72, v96, v97
	s_waitcnt lgkmcnt(2)
	v_add_f32_e32 v70, v70, v71
	ds_bpermute_b32 v71, v61, v70
	s_waitcnt lgkmcnt(2)
	v_add_f32_e32 v73, v69, v98
	ds_bpermute_b32 v69, v60, v72
	s_waitcnt lgkmcnt(2)
	v_add_f32_e32 v74, v74, v75
	ds_bpermute_b32 v75, v62, v74
	s_waitcnt lgkmcnt(2)
	v_add_f32_e32 v70, v70, v71
	ds_bpermute_b32 v71, v62, v70
	s_waitcnt lgkmcnt(2)
	v_add_f32_e32 v69, v72, v69
	ds_bpermute_b32 v72, v61, v69
	s_waitcnt lgkmcnt(2)
	v_add_f32_e32 v74, v74, v75
	ds_bpermute_b32 v75, v63, v74
	s_waitcnt lgkmcnt(2)
	v_add_f32_e32 v70, v70, v71
	ds_bpermute_b32 v71, v63, v70
	s_waitcnt lgkmcnt(2)
	v_add_f32_e32 v69, v69, v72
	ds_bpermute_b32 v72, v62, v69
	s_waitcnt lgkmcnt(2)
	v_add_f32_e32 v75, v74, v75
	ds_bpermute_b32 v92, v64, v75
	s_waitcnt lgkmcnt(2)
	v_add_f32_e32 v70, v70, v71
	ds_bpermute_b32 v71, v64, v70
	s_waitcnt lgkmcnt(2)
	v_add_f32_e32 v69, v69, v72
	ds_bpermute_b32 v72, v63, v69
	ds_bpermute_b32 v74, v65, v73
	s_waitcnt lgkmcnt(2)
	v_add_f32_e32 v70, v70, v71
	ds_bpermute_b32 v94, v65, v70
	v_add_f32_e32 v71, v75, v92
	s_waitcnt lgkmcnt(2)
	v_add_f32_e32 v69, v69, v72
	ds_bpermute_b32 v93, v64, v69
	ds_bpermute_b32 v72, v65, v71
	s_waitcnt lgkmcnt(2)
	v_add_f32_e32 v70, v70, v94
	v_fmamk_f32 v70, v70, 0x3a800000, v67
	v_mul_f32_e32 v75, 0x4b800000, v70
	v_cmp_gt_f32_e64 s[8:9], s18, v70
	s_waitcnt lgkmcnt(1)
	v_add_f32_e32 v69, v69, v93
	v_cndmask_b32_e64 v70, v70, v75, s[8:9]
	v_rsq_f32_e32 v75, v70
	ds_bpermute_b32 v70, v65, v69
	v_mul_f32_e32 v92, 0x45800000, v75
	v_cndmask_b32_e64 v92, v75, v92, s[8:9]
	v_pk_mul_f32 v[76:77], v[76:77], v[92:93] op_sel_hi:[1,0]
	v_pk_mul_f32 v[78:79], v[78:79], v[92:93] op_sel_hi:[1,0]
	v_cvt_pk_bf16_f32 v76, v76, v77
	v_cvt_pk_bf16_f32 v77, v78, v79
	global_store_dwordx2 v[58:59], v[76:77], off sc1
	v_pk_mul_f32 v[76:77], v[80:81], v[92:93] op_sel_hi:[1,0]
	v_pk_mul_f32 v[78:79], v[82:83], v[92:93] op_sel_hi:[1,0]
	v_cvt_pk_bf16_f32 v76, v76, v77
	v_cvt_pk_bf16_f32 v77, v78, v79
	global_store_dwordx2 v[58:59], v[76:77], off offset:512 sc1
	v_pk_mul_f32 v[76:77], v[84:85], v[92:93] op_sel_hi:[1,0]
	v_pk_mul_f32 v[78:79], v[86:87], v[92:93] op_sel_hi:[1,0]
	v_cvt_pk_bf16_f32 v76, v76, v77
	v_cvt_pk_bf16_f32 v77, v78, v79
	global_store_dwordx2 v[58:59], v[76:77], off offset:1024 sc1
	v_pk_mul_f32 v[76:77], v[88:89], v[92:93] op_sel_hi:[1,0]
	v_pk_mul_f32 v[78:79], v[90:91], v[92:93] op_sel_hi:[1,0]
	v_cvt_pk_bf16_f32 v76, v76, v77
	v_cvt_pk_bf16_f32 v77, v78, v79
	global_store_dwordx2 v[58:59], v[76:77], off offset:1536 sc1
	s_and_saveexec_b64 s[8:9], s[6:7]
	s_cbranch_execnz .Lrnp3_a1426
	s_or_b64 exec, exec, s[8:9]
	s_and_saveexec_b64 s[6:7], s[0:1]
	s_cbranch_execnz .Lrnp3_a1427
